# GEMM bursts: MFMAs reordered so the two K-halves of each accumulator issue back to back (SrcC forwarding chain)
# baseline (speedup 1.0000x reference)
; #define PG8_STAGE(bufoff, gbase, voff) do { _Pragma("unroll") for (int _i = 0; _i < 2; ++_i) \
;         __builtin_amdgcn_global_load_lds((const unsigned*)((const char*)(gbase) + (voff)[_i]), (PG8_LAS unsigned*)(lds + (bufoff) + ldsw + _i * 8192), 16, 0, 0); } while (0)
; #define PG8_LDA(dst, b, h) do { _Pragma("unroll") for (int m = 0; m < 4; ++m) _Pragma("unroll") for (int k = 0; k < 2; ++k) dst[m][k] = *(const PG8_LAS bf16x8*)(lds + PG8_SA(b, h) + aoff + m * 2048 + k * 1024); } while (0)
; #define PG8_LDB(dst, b, h) do { _Pragma("unroll") for (int n = 0; n < 2; ++n) _Pragma("unroll") for (int k = 0; k < 2; ++k) dst[n][k] = *(const PG8_LAS bf16x8*)(lds + PG8_SB(b, h) + boff + n * 2048 + k * 1024); } while (0)
; #define PG8_WAIT_V(n) asm volatile("s_waitcnt vmcnt(" #n ")" ::: "memory")
; #define PG8_WAIT_L(n) asm volatile("s_waitcnt lgkmcnt(" #n ")" ::: "memory")
; #define PG8_BAR __builtin_amdgcn_s_barrier()
; #define PG8_SCHED __builtin_amdgcn_sched_barrier(0)
; template <class Epi, class Sched, bool ALIGN_EPI = false, bool SP2 = false>
; __device__ __forceinline__ void gemm_phase(PG8_LAS unsigned char* lds, const Gemm g, const Sched& S, const Epi& E) {
;     ...
;             const char* a1 = cA + (g.gstrA ? (size_t)(t >> 2) * g.gstrA + (size_t)(t & 3) * kstep : (size_t)t * kstep) + kstep;
;             const char* a2 = last ? nA : cA + (g.gstrA ? (size_t)((t + 2) >> 2) * g.gstrA + (size_t)((t + 2) & 3) * kstep : (size_t)(t + 2) * kstep); const char* b2 = last ? nB : cB + (size_t)(t + 2) * kstep;
;             const char* a3 = a2 + kstep; const char* b3 = b2 + kstep;
;             if (last && has_next) S.a_ready(nxt);
;             if constexpr (Epi::HAS_PREFETCH) { if (t == nt - 4) E.prefetch(cur, tid, wid); }
;             if constexpr (SP2) {
;             PG8_LDB(B0, 0, 0); PG8_LDB(B1, 0, 1); PG8_SCHED; PG8_LDA(At, 0, 0); PG8_STAGE(PG8_SA(1, 1), a1 + hstepA, voffA);
;             PG8_WAIT_V(8); PG8_WAIT_L(0); PG8_BAR; PG8_MMA(0, 0, At, B0); PG8_MMA(0, 1, At, B1); PG8_BAR; PG8_SCHED;
;             PG8_LDA(At, 0, 1); PG8_STAGE(PG8_SB(0, 0), b2, voffB); PG8_STAGE(PG8_SB(0, 1), b2 + hstep, voffB); PG8_STAGE(PG8_SA(0, 0), a2, voffA);
;             PG8_WAIT_V(8); PG8_WAIT_L(0); PG8_BAR; PG8_MMA(1, 0, At, B0); PG8_MMA(1, 1, At, B1); PG8_BAR; PG8_SCHED;
.LBB0_53:
	s_add_u32 s14, s82, 0xfffc0080
	s_addc_u32 s15, s83, -1
	s_add_i32 s38, 0, 0x10000
	s_cmp_eq_u32 s52, 12
	s_cselect_b32 s15, s18, s15
	s_cselect_b32 s14, s24, s14
	s_cselect_b32 s41, s26, s36
	s_cselect_b32 s40, s30, s34
	s_add_i32 s56, 0, 0x14000
	v_add_u32_e32 v44, s38, v174
	v_add_u32_e32 v157, s56, v174
	ds_read_b128 v[24:27], v44
	ds_read_b128 v[28:31], v44 offset:1024
	ds_read_b128 v[40:43], v44 offset:2048
	ds_read_b128 v[44:47], v44 offset:3072
	ds_read_b128 v[186:189], v157
	ds_read_b128 v[190:193], v157 offset:1024
	ds_read_b128 v[194:197], v157 offset:2048
	ds_read_b128 v[198:201], v157 offset:3072
	v_lshl_add_u64 v[170:171], s[82:83], 0, v[152:153]
	s_add_i32 m0, s3, 0xc000
	ds_read_b128 v[202:205], v184
	ds_read_b128 v[206:209], v184 offset:1024
	ds_read_b128 v[214:217], v184 offset:2048
	ds_read_b128 v[218:221], v184 offset:3072
	ds_read_b128 v[222:225], v184 offset:4096
	ds_read_b128 v[240:243], v184 offset:5120
	ds_read_b128 v[244:247], v184 offset:6144
	ds_read_b128 v[248:251], v184 offset:7168
	global_load_lds_dwordx4 v[170:171], off
	v_lshl_add_u64 v[170:171], s[82:83], 0, v[154:155]
	s_add_i32 m0, s3, 0xe000
	s_nop 0
	global_load_lds_dwordx4 v[170:171], off
	s_waitcnt vmcnt(8)
	s_waitcnt lgkmcnt(0)
	s_barrier
	s_setprio 1
	s_waitcnt lgkmcnt(0)
	v_mfma_f32_16x16x32_bf16 v[140:143], v[24:27], v[202:205], v[140:143]
	v_mfma_f32_16x16x32_bf16 v[140:143], v[28:31], v[206:209], v[140:143]
	v_mfma_f32_16x16x32_bf16 v[136:139], v[40:43], v[202:205], v[136:139]
	v_mfma_f32_16x16x32_bf16 v[136:139], v[44:47], v[206:209], v[136:139]
	v_mfma_f32_16x16x32_bf16 v[124:127], v[24:27], v[214:217], v[124:127]
	v_mfma_f32_16x16x32_bf16 v[124:127], v[28:31], v[218:221], v[124:127]
	v_mfma_f32_16x16x32_bf16 v[120:123], v[40:43], v[214:217], v[120:123]
	v_mfma_f32_16x16x32_bf16 v[120:123], v[44:47], v[218:221], v[120:123]
	v_mfma_f32_16x16x32_bf16 v[108:111], v[24:27], v[222:225], v[108:111]
	v_mfma_f32_16x16x32_bf16 v[108:111], v[28:31], v[240:243], v[108:111]
	v_mfma_f32_16x16x32_bf16 v[104:107], v[40:43], v[222:225], v[104:107]
	v_mfma_f32_16x16x32_bf16 v[104:107], v[44:47], v[240:243], v[104:107]
	v_mfma_f32_16x16x32_bf16 v[92:95], v[24:27], v[244:247], v[92:95]
	v_mfma_f32_16x16x32_bf16 v[92:95], v[28:31], v[248:251], v[92:95]
	v_mfma_f32_16x16x32_bf16 v[88:91], v[40:43], v[244:247], v[88:91]
	v_mfma_f32_16x16x32_bf16 v[88:91], v[44:47], v[248:251], v[88:91]
	s_setprio 0
	s_setprio 1
	v_mfma_f32_16x16x32_bf16 v[132:135], v[186:189], v[202:205], v[132:135]
	v_mfma_f32_16x16x32_bf16 v[132:135], v[190:193], v[206:209], v[132:135]
	v_mfma_f32_16x16x32_bf16 v[128:131], v[194:197], v[202:205], v[128:131]
	v_mfma_f32_16x16x32_bf16 v[128:131], v[198:201], v[206:209], v[128:131]
	v_mfma_f32_16x16x32_bf16 v[116:119], v[186:189], v[214:217], v[116:119]
	v_mfma_f32_16x16x32_bf16 v[116:119], v[190:193], v[218:221], v[116:119]
	v_mfma_f32_16x16x32_bf16 v[112:115], v[194:197], v[214:217], v[112:115]
	v_mfma_f32_16x16x32_bf16 v[112:115], v[198:201], v[218:221], v[112:115]
	v_mfma_f32_16x16x32_bf16 v[100:103], v[186:189], v[222:225], v[100:103]
	v_mfma_f32_16x16x32_bf16 v[100:103], v[190:193], v[240:243], v[100:103]
	v_mfma_f32_16x16x32_bf16 v[96:99], v[194:197], v[222:225], v[96:99]
	v_mfma_f32_16x16x32_bf16 v[96:99], v[198:201], v[240:243], v[96:99]
	v_mfma_f32_16x16x32_bf16 v[84:87], v[186:189], v[244:247], v[84:87]
	v_mfma_f32_16x16x32_bf16 v[84:87], v[190:193], v[248:251], v[84:87]
	v_mfma_f32_16x16x32_bf16 v[80:83], v[194:197], v[244:247], v[80:83]
	v_mfma_f32_16x16x32_bf16 v[80:83], v[198:201], v[248:251], v[80:83]
	s_setprio 0
	s_barrier
	s_add_i32 s38, s38, s2
	v_lshl_add_u64 v[170:171], s[40:41], 0, v[146:147]
	s_mov_b32 m0, s38
	ds_read_b128 v[202:205], v184 offset:16384
	ds_read_b128 v[206:209], v184 offset:17408
	ds_read_b128 v[214:217], v184 offset:18432
	ds_read_b128 v[218:221], v184 offset:19456
	ds_read_b128 v[222:225], v184 offset:20480
	ds_read_b128 v[240:243], v184 offset:21504
	ds_read_b128 v[244:247], v184 offset:22528
	ds_read_b128 v[248:251], v184 offset:23552
	global_load_lds_dwordx4 v[170:171], off
	s_add_i32 m0, s38, 0x2000
	s_add_u32 s54, s40, 0x40000
	v_lshl_add_u64 v[210:211], s[40:41], 0, v[150:151]
	s_addc_u32 s55, s41, 0
	s_add_i32 s38, s56, s2
	global_load_lds_dwordx4 v[210:211], off
	v_lshl_add_u64 v[252:253], s[54:55], 0, v[146:147]
	s_mov_b32 m0, s38
	v_lshl_add_u64 v[234:235], s[14:15], 0, v[148:149]
	global_load_lds_dwordx4 v[252:253], off
	v_lshl_add_u64 v[252:253], s[54:55], 0, v[150:151]
	s_add_i32 m0, s38, 0x2000
	s_nop 0
	global_load_lds_dwordx4 v[252:253], off
	v_lshl_add_u64 v[252:253], s[14:15], 0, v[144:145]
	s_mov_b32 m0, s3
	s_nop 0
	global_load_lds_dwordx4 v[252:253], off
	s_mov_b32 m0, s16
	s_nop 0
	global_load_lds_dwordx4 v[234:235], off
	s_waitcnt vmcnt(8)
	s_waitcnt lgkmcnt(0)
	s_barrier
; #define PG8_STAGE(bufoff, gbase, voff) do { _Pragma("unroll") for (int _i = 0; _i < 2; ++_i) \
;         __builtin_amdgcn_global_load_lds((const unsigned*)((const char*)(gbase) + (voff)[_i]), (PG8_LAS unsigned*)(lds + (bufoff) + ldsw + _i * 8192), 16, 0, 0); } while (0)
; #define PG8_LDA(dst, b, h) do { _Pragma("unroll") for (int m = 0; m < 4; ++m) _Pragma("unroll") for (int k = 0; k < 2; ++k) dst[m][k] = *(const PG8_LAS bf16x8*)(lds + PG8_SA(b, h) + aoff + m * 2048 + k * 1024); } while (0)
; #define PG8_LDB(dst, b, h) do { _Pragma("unroll") for (int n = 0; n < 2; ++n) _Pragma("unroll") for (int k = 0; k < 2; ++k) dst[n][k] = *(const PG8_LAS bf16x8*)(lds + PG8_SB(b, h) + boff + n * 2048 + k * 1024); } while (0)
; #define PG8_MMA(ai, bj, At, Bt) do { __builtin_amdgcn_s_setprio(1); _Pragma("unroll") for (int m = 0; m < 4; ++m) _Pragma("unroll") for (int n = 0; n < 2; ++n) _Pragma("unroll") for (int k = 0; k < 2; ++k) \
;         acc[ai][bj][m][n] = __builtin_amdgcn_mfma_f32_16x16x32_bf16(Bt[n][k], At[m][k], acc[ai][bj][m][n], 0, 0, 0); __builtin_amdgcn_s_setprio(0); } while (0)
; #define PG8_WAIT_V(n) asm volatile("s_waitcnt vmcnt(" #n ")" ::: "memory")
; #define PG8_WAIT_L(n) asm volatile("s_waitcnt lgkmcnt(" #n ")" ::: "memory")
; #define PG8_BAR __builtin_amdgcn_s_barrier()
; #define PG8_SCHED __builtin_amdgcn_sched_barrier(0)
; template <class Epi, class Sched, bool ALIGN_EPI = false, bool SP2 = false>
; __device__ __forceinline__ void gemm_phase(PG8_LAS unsigned char* lds, const Gemm g, const Sched& S, const Epi& E) {
;     ...
;             PG8_WAIT_V(8); PG8_WAIT_L(0); PG8_BAR; PG8_MMA(1, 0, At, B0); PG8_MMA(1, 1, At, B1); PG8_BAR; PG8_SCHED;
;             PG8_LDB(B0, 1, 0); PG8_LDB(B1, 1, 1); PG8_SCHED; PG8_LDA(At, 1, 0); PG8_STAGE(PG8_SA(0, 1), a2 + hstepA, voffA);
;             PG8_WAIT_V(8); PG8_WAIT_L(0); PG8_BAR; PG8_MMA(0, 0, At, B0); PG8_MMA(0, 1, At, B1); PG8_BAR; PG8_SCHED;
	s_setprio 1
	s_waitcnt lgkmcnt(0)
	v_mfma_f32_16x16x32_bf16 v[76:79], v[24:27], v[202:205], v[76:79]
	v_mfma_f32_16x16x32_bf16 v[76:79], v[28:31], v[206:209], v[76:79]
	v_mfma_f32_16x16x32_bf16 v[72:75], v[40:43], v[202:205], v[72:75]
	v_mfma_f32_16x16x32_bf16 v[72:75], v[44:47], v[206:209], v[72:75]
	v_mfma_f32_16x16x32_bf16 v[60:63], v[24:27], v[214:217], v[60:63]
	v_mfma_f32_16x16x32_bf16 v[60:63], v[28:31], v[218:221], v[60:63]
	v_mfma_f32_16x16x32_bf16 v[56:59], v[40:43], v[214:217], v[56:59]
	v_mfma_f32_16x16x32_bf16 v[56:59], v[44:47], v[218:221], v[56:59]
	v_mfma_f32_16x16x32_bf16 v[36:39], v[24:27], v[222:225], v[36:39]
	v_mfma_f32_16x16x32_bf16 v[36:39], v[28:31], v[240:243], v[36:39]
	v_mfma_f32_16x16x32_bf16 v[32:35], v[40:43], v[222:225], v[32:35]
	v_mfma_f32_16x16x32_bf16 v[32:35], v[44:47], v[240:243], v[32:35]
	v_mfma_f32_16x16x32_bf16 v[12:15], v[24:27], v[244:247], v[12:15]
	v_mfma_f32_16x16x32_bf16 v[12:15], v[28:31], v[248:251], v[12:15]
	v_mfma_f32_16x16x32_bf16 v[8:11], v[40:43], v[244:247], v[8:11]
	v_mfma_f32_16x16x32_bf16 v[8:11], v[44:47], v[248:251], v[8:11]
	s_setprio 0
	s_setprio 1
	v_mfma_f32_16x16x32_bf16 v[20:23], v[186:189], v[222:225], v[20:23]
	v_mfma_f32_16x16x32_bf16 v[16:19], v[194:197], v[222:225], v[16:19]
	v_mfma_f32_16x16x32_bf16 v[4:7], v[186:189], v[244:247], v[4:7]
	v_mfma_f32_16x16x32_bf16 v[0:3], v[194:197], v[244:247], v[0:3]
	v_mfma_f32_16x16x32_bf16 v[24:27], v[186:189], v[202:205], v[68:71]
	v_mfma_f32_16x16x32_bf16 v[28:31], v[194:197], v[202:205], v[64:67]
	v_mfma_f32_16x16x32_bf16 v[40:43], v[186:189], v[214:217], v[52:55]
	v_mfma_f32_16x16x32_bf16 v[44:47], v[194:197], v[214:217], v[48:51]
	v_mfma_f32_16x16x32_bf16 v[20:23], v[190:193], v[240:243], v[20:23]
	v_mfma_f32_16x16x32_bf16 v[16:19], v[198:201], v[240:243], v[16:19]
	v_mfma_f32_16x16x32_bf16 v[4:7], v[190:193], v[248:251], v[4:7]
	v_mfma_f32_16x16x32_bf16 v[0:3], v[198:201], v[248:251], v[0:3]
	v_mfma_f32_16x16x32_bf16 v[24:27], v[190:193], v[206:209], v[24:27]
	v_mfma_f32_16x16x32_bf16 v[28:31], v[198:201], v[206:209], v[28:31]
	v_mfma_f32_16x16x32_bf16 v[40:43], v[190:193], v[218:221], v[40:43]
	v_mfma_f32_16x16x32_bf16 v[44:47], v[198:201], v[218:221], v[44:47]
	s_setprio 0
	s_barrier
	s_add_i32 s38, 0, 0x18000
	s_add_i32 s54, 0, 0x1c000
	v_add_u32_e32 v68, s38, v174
	v_add_u32_e32 v157, s54, v174
	ds_read_b128 v[48:51], v68
	ds_read_b128 v[52:55], v68 offset:1024
	ds_read_b128 v[64:67], v68 offset:2048
	ds_read_b128 v[68:71], v68 offset:3072
	ds_read_b128 v[186:189], v157
	ds_read_b128 v[190:193], v157 offset:1024
	ds_read_b128 v[194:197], v157 offset:2048
	ds_read_b128 v[198:201], v157 offset:3072
	s_add_u32 s14, s14, 0x40000
	s_addc_u32 s15, s15, 0
	s_mov_b32 m0, s17
	v_lshl_add_u64 v[176:177], s[14:15], 0, v[144:145]
	ds_read_b128 v[202:205], v184 offset:32768
	ds_read_b128 v[206:209], v184 offset:33792
	ds_read_b128 v[214:217], v184 offset:34816
	ds_read_b128 v[218:221], v184 offset:35840
	ds_read_b128 v[222:225], v184 offset:36864
	ds_read_b128 v[240:243], v184 offset:37888
	ds_read_b128 v[244:247], v184 offset:38912
	ds_read_b128 v[248:251], v184 offset:39936
	global_load_lds_dwordx4 v[176:177], off
	v_lshl_add_u64 v[176:177], s[14:15], 0, v[148:149]
	s_mov_b32 m0, s20
	s_nop 0
	global_load_lds_dwordx4 v[176:177], off
	s_waitcnt vmcnt(8)
	s_waitcnt lgkmcnt(0)
	s_barrier
	s_setprio 1
	s_waitcnt lgkmcnt(0)
	v_mfma_f32_16x16x32_bf16 v[140:143], v[48:51], v[202:205], v[140:143]
	v_mfma_f32_16x16x32_bf16 v[140:143], v[52:55], v[206:209], v[140:143]
	v_mfma_f32_16x16x32_bf16 v[136:139], v[64:67], v[202:205], v[136:139]
	v_mfma_f32_16x16x32_bf16 v[136:139], v[68:71], v[206:209], v[136:139]
	v_mfma_f32_16x16x32_bf16 v[124:127], v[48:51], v[214:217], v[124:127]
	v_mfma_f32_16x16x32_bf16 v[124:127], v[52:55], v[218:221], v[124:127]
	v_mfma_f32_16x16x32_bf16 v[120:123], v[64:67], v[214:217], v[120:123]
	v_mfma_f32_16x16x32_bf16 v[120:123], v[68:71], v[218:221], v[120:123]
	v_mfma_f32_16x16x32_bf16 v[108:111], v[48:51], v[222:225], v[108:111]
	v_mfma_f32_16x16x32_bf16 v[108:111], v[52:55], v[240:243], v[108:111]
	v_mfma_f32_16x16x32_bf16 v[104:107], v[64:67], v[222:225], v[104:107]
	v_mfma_f32_16x16x32_bf16 v[104:107], v[68:71], v[240:243], v[104:107]
	v_mfma_f32_16x16x32_bf16 v[92:95], v[48:51], v[244:247], v[92:95]
	v_mfma_f32_16x16x32_bf16 v[92:95], v[52:55], v[248:251], v[92:95]
	v_mfma_f32_16x16x32_bf16 v[88:91], v[64:67], v[244:247], v[88:91]
	v_mfma_f32_16x16x32_bf16 v[88:91], v[68:71], v[248:251], v[88:91]
	s_setprio 0
	s_setprio 1
	v_mfma_f32_16x16x32_bf16 v[132:135], v[186:189], v[202:205], v[132:135]
	v_mfma_f32_16x16x32_bf16 v[132:135], v[190:193], v[206:209], v[132:135]
	v_mfma_f32_16x16x32_bf16 v[128:131], v[194:197], v[202:205], v[128:131]
	v_mfma_f32_16x16x32_bf16 v[128:131], v[198:201], v[206:209], v[128:131]
	v_mfma_f32_16x16x32_bf16 v[116:119], v[186:189], v[214:217], v[116:119]
	v_mfma_f32_16x16x32_bf16 v[116:119], v[190:193], v[218:221], v[116:119]
	v_mfma_f32_16x16x32_bf16 v[112:115], v[194:197], v[214:217], v[112:115]
	v_mfma_f32_16x16x32_bf16 v[112:115], v[198:201], v[218:221], v[112:115]
	v_mfma_f32_16x16x32_bf16 v[100:103], v[186:189], v[222:225], v[100:103]
	v_mfma_f32_16x16x32_bf16 v[100:103], v[190:193], v[240:243], v[100:103]
	v_mfma_f32_16x16x32_bf16 v[96:99], v[194:197], v[222:225], v[96:99]
	v_mfma_f32_16x16x32_bf16 v[96:99], v[198:201], v[240:243], v[96:99]
	v_mfma_f32_16x16x32_bf16 v[84:87], v[186:189], v[244:247], v[84:87]
	v_mfma_f32_16x16x32_bf16 v[84:87], v[190:193], v[248:251], v[84:87]
	v_mfma_f32_16x16x32_bf16 v[80:83], v[194:197], v[244:247], v[80:83]
	v_mfma_f32_16x16x32_bf16 v[80:83], v[198:201], v[248:251], v[80:83]
	s_setprio 0
	s_barrier
; #define PG8_STAGE(bufoff, gbase, voff) do { _Pragma("unroll") for (int _i = 0; _i < 2; ++_i) \
;         __builtin_amdgcn_global_load_lds((const unsigned*)((const char*)(gbase) + (voff)[_i]), (PG8_LAS unsigned*)(lds + (bufoff) + ldsw + _i * 8192), 16, 0, 0); } while (0)
; #define PG8_LDA(dst, b, h) do { _Pragma("unroll") for (int m = 0; m < 4; ++m) _Pragma("unroll") for (int k = 0; k < 2; ++k) dst[m][k] = *(const PG8_LAS bf16x8*)(lds + PG8_SA(b, h) + aoff + m * 2048 + k * 1024); } while (0)
; #define PG8_MMA(ai, bj, At, Bt) do { __builtin_amdgcn_s_setprio(1); _Pragma("unroll") for (int m = 0; m < 4; ++m) _Pragma("unroll") for (int n = 0; n < 2; ++n) _Pragma("unroll") for (int k = 0; k < 2; ++k) \
;         acc[ai][bj][m][n] = __builtin_amdgcn_mfma_f32_16x16x32_bf16(Bt[n][k], At[m][k], acc[ai][bj][m][n], 0, 0, 0); __builtin_amdgcn_s_setprio(0); } while (0)
; #define PG8_WAIT_V(n) asm volatile("s_waitcnt vmcnt(" #n ")" ::: "memory")
; #define PG8_WAIT_L(n) asm volatile("s_waitcnt lgkmcnt(" #n ")" ::: "memory")
; #define PG8_BAR __builtin_amdgcn_s_barrier()
; #define PG8_SCHED __builtin_amdgcn_sched_barrier(0)
; template <class Epi, class Sched, bool ALIGN_EPI = false, bool SP2 = false>
; __device__ __forceinline__ void gemm_phase(PG8_LAS unsigned char* lds, const Gemm g, const Sched& S, const Epi& E) {
;     ...
;         for (int t = 0; t < nt; t += 2) {
;     ...
;             PG8_LDA(At, 1, 1); PG8_STAGE(PG8_SB(1, 0), b3, voffB); PG8_STAGE(PG8_SB(1, 1), b3 + hstep, voffB); PG8_STAGE(PG8_SA(1, 0), a3, voffA);
;             PG8_WAIT_V(8); PG8_WAIT_L(0); PG8_BAR; PG8_MMA(1, 0, At, B0); PG8_MMA(1, 1, At, B1); PG8_BAR; PG8_SCHED;
;     ...
;         if constexpr (ALIGN_EPI) { if (wr == 0) PG8_BAR; }
	s_add_i32 s14, s38, s2
	v_lshl_add_u64 v[170:171], v[170:171], 0, s[22:23]
	s_mov_b32 m0, s14
	ds_read_b128 v[202:205], v184 offset:49152
	ds_read_b128 v[206:209], v184 offset:50176
	ds_read_b128 v[214:217], v184 offset:51200
	ds_read_b128 v[218:221], v184 offset:52224
	ds_read_b128 v[222:225], v184 offset:53248
	ds_read_b128 v[240:243], v184 offset:54272
	ds_read_b128 v[244:247], v184 offset:55296
	ds_read_b128 v[248:251], v184 offset:56320
	global_load_lds_dwordx4 v[170:171], off
	s_add_i32 m0, s14, 0x2000
	s_add_u32 s14, s40, 0x40080
	v_lshl_add_u64 v[170:171], v[210:211], 0, s[22:23]
	s_addc_u32 s15, s41, 0
	s_add_i32 s38, s54, s2
	global_load_lds_dwordx4 v[170:171], off
	v_lshl_add_u64 v[170:171], s[14:15], 0, v[146:147]
	s_mov_b32 m0, s38
	s_nop 0
	global_load_lds_dwordx4 v[170:171], off
	v_lshl_add_u64 v[170:171], s[14:15], 0, v[150:151]
	s_add_i32 m0, s38, 0x2000
	s_nop 0
	global_load_lds_dwordx4 v[170:171], off
	v_lshl_add_u64 v[170:171], v[252:253], 0, s[22:23]
	s_mov_b32 m0, s29
	s_nop 0
	global_load_lds_dwordx4 v[170:171], off
	v_lshl_add_u64 v[170:171], v[234:235], 0, s[22:23]
	s_mov_b32 m0, s31
	s_nop 0
	global_load_lds_dwordx4 v[170:171], off
	s_waitcnt vmcnt(8)
	s_waitcnt lgkmcnt(0)
	s_barrier
	s_setprio 1
	s_waitcnt lgkmcnt(0)
	v_mfma_f32_16x16x32_bf16 v[76:79], v[48:51], v[202:205], v[76:79]
	v_mfma_f32_16x16x32_bf16 v[76:79], v[52:55], v[206:209], v[76:79]
	v_mfma_f32_16x16x32_bf16 v[72:75], v[64:67], v[202:205], v[72:75]
	v_mfma_f32_16x16x32_bf16 v[72:75], v[68:71], v[206:209], v[72:75]
	v_mfma_f32_16x16x32_bf16 v[60:63], v[48:51], v[214:217], v[60:63]
	v_mfma_f32_16x16x32_bf16 v[60:63], v[52:55], v[218:221], v[60:63]
	v_mfma_f32_16x16x32_bf16 v[56:59], v[64:67], v[214:217], v[56:59]
	v_mfma_f32_16x16x32_bf16 v[56:59], v[68:71], v[218:221], v[56:59]
	v_mfma_f32_16x16x32_bf16 v[36:39], v[48:51], v[222:225], v[36:39]
	v_mfma_f32_16x16x32_bf16 v[36:39], v[52:55], v[240:243], v[36:39]
	v_mfma_f32_16x16x32_bf16 v[32:35], v[64:67], v[222:225], v[32:35]
	v_mfma_f32_16x16x32_bf16 v[32:35], v[68:71], v[240:243], v[32:35]
	v_mfma_f32_16x16x32_bf16 v[12:15], v[48:51], v[244:247], v[12:15]
	v_mfma_f32_16x16x32_bf16 v[12:15], v[52:55], v[248:251], v[12:15]
	v_mfma_f32_16x16x32_bf16 v[8:11], v[64:67], v[244:247], v[8:11]
	v_mfma_f32_16x16x32_bf16 v[8:11], v[68:71], v[248:251], v[8:11]
	s_setprio 0
	s_setprio 1
	v_mfma_f32_16x16x32_bf16 v[24:27], v[186:189], v[202:205], v[24:27]
	v_mfma_f32_16x16x32_bf16 v[68:71], v[190:193], v[206:209], v[24:27]
	v_mfma_f32_16x16x32_bf16 v[24:27], v[194:197], v[202:205], v[28:31]
	v_mfma_f32_16x16x32_bf16 v[64:67], v[198:201], v[206:209], v[24:27]
	v_mfma_f32_16x16x32_bf16 v[24:27], v[186:189], v[214:217], v[40:43]
	v_mfma_f32_16x16x32_bf16 v[52:55], v[190:193], v[218:221], v[24:27]
	v_mfma_f32_16x16x32_bf16 v[24:27], v[194:197], v[214:217], v[44:47]
	v_mfma_f32_16x16x32_bf16 v[20:23], v[186:189], v[222:225], v[20:23]
	v_mfma_f32_16x16x32_bf16 v[16:19], v[194:197], v[222:225], v[16:19]
	v_mfma_f32_16x16x32_bf16 v[4:7], v[186:189], v[244:247], v[4:7]
	v_mfma_f32_16x16x32_bf16 v[0:3], v[194:197], v[244:247], v[0:3]
	v_mfma_f32_16x16x32_bf16 v[48:51], v[198:201], v[218:221], v[24:27]
	v_mfma_f32_16x16x32_bf16 v[20:23], v[190:193], v[240:243], v[20:23]
	v_mfma_f32_16x16x32_bf16 v[16:19], v[198:201], v[240:243], v[16:19]
	v_mfma_f32_16x16x32_bf16 v[4:7], v[190:193], v[248:251], v[4:7]
	v_mfma_f32_16x16x32_bf16 v[0:3], v[198:201], v[248:251], v[0:3]
	s_setprio 0
	s_barrier
	s_add_i32 s52, s52, 2
	s_add_u32 s82, s82, 0x100
	s_addc_u32 s83, s83, 0
	s_add_u32 s34, s34, 0x100
	s_addc_u32 s36, s36, 0
	s_cmp_gt_u32 s52, 13
	s_cbranch_scc0 .LBB0_53
	s_and_b64 vcc, exec, s[72:73]
	s_cbranch_vccz .LBB0_56
	s_barrier

; #define PG8_STAGE(bufoff, gbase, voff) do { _Pragma("unroll") for (int _i = 0; _i < 2; ++_i) \
;         __builtin_amdgcn_global_load_lds((const unsigned*)((const char*)(gbase) + (voff)[_i]), (PG8_LAS unsigned*)(lds + (bufoff) + ldsw + _i * 8192), 16, 0, 0); } while (0)
; #define PG8_LDA(dst, b, h) do { _Pragma("unroll") for (int m = 0; m < 4; ++m) _Pragma("unroll") for (int k = 0; k < 2; ++k) dst[m][k] = *(const PG8_LAS bf16x8*)(lds + PG8_SA(b, h) + aoff + m * 2048 + k * 1024); } while (0)
; #define PG8_LDB(dst, b, h) do { _Pragma("unroll") for (int n = 0; n < 2; ++n) _Pragma("unroll") for (int k = 0; k < 2; ++k) dst[n][k] = *(const PG8_LAS bf16x8*)(lds + PG8_SB(b, h) + boff + n * 2048 + k * 1024); } while (0)
; #define PG8_WAIT_V(n) asm volatile("s_waitcnt vmcnt(" #n ")" ::: "memory")
; #define PG8_WAIT_L(n) asm volatile("s_waitcnt lgkmcnt(" #n ")" ::: "memory")
; #define PG8_BAR __builtin_amdgcn_s_barrier()
; #define PG8_SCHED __builtin_amdgcn_sched_barrier(0)
; template <class Epi, class Sched, bool ALIGN_EPI = false, bool SP2 = false>
; __device__ __forceinline__ void gemm_phase(PG8_LAS unsigned char* lds, const Gemm g, const Sched& S, const Epi& E) {
;     ...
;             const char* a1 = cA + (g.gstrA ? (size_t)(t >> 2) * g.gstrA + (size_t)(t & 3) * kstep : (size_t)t * kstep) + kstep;
;             const char* a2 = last ? nA : cA + (g.gstrA ? (size_t)((t + 2) >> 2) * g.gstrA + (size_t)((t + 2) & 3) * kstep : (size_t)(t + 2) * kstep); const char* b2 = last ? nB : cB + (size_t)(t + 2) * kstep;
;             const char* a3 = a2 + kstep; const char* b3 = b2 + kstep;
;             if (last && has_next) S.a_ready(nxt);
;             if constexpr (Epi::HAS_PREFETCH) { if (t == nt - 4) E.prefetch(cur, tid, wid); }
;             if constexpr (SP2) {
;             PG8_LDB(B0, 0, 0); PG8_LDB(B1, 0, 1); PG8_SCHED; PG8_LDA(At, 0, 0); PG8_STAGE(PG8_SA(1, 1), a1 + hstepA, voffA);
;             PG8_WAIT_V(8); PG8_WAIT_L(0); PG8_BAR; PG8_MMA(0, 0, At, B0); PG8_MMA(0, 1, At, B1); PG8_BAR; PG8_SCHED;
;             PG8_LDA(At, 0, 1); PG8_STAGE(PG8_SB(0, 0), b2, voffB); PG8_STAGE(PG8_SB(0, 1), b2 + hstep, voffB); PG8_STAGE(PG8_SA(0, 0), a2, voffA);
;             PG8_WAIT_V(8); PG8_WAIT_L(0); PG8_BAR; PG8_MMA(1, 0, At, B0); PG8_MMA(1, 1, At, B1); PG8_BAR; PG8_SCHED;
.LBB0_119:
	s_add_u32 s14, s74, 0xfffc0080
	s_addc_u32 s15, s75, -1
	s_add_i32 s35, 0, 0x10000
	s_cmp_eq_u32 s34, 12
	s_cselect_b32 s15, s24, s15
	s_cselect_b32 s14, s26, s14
	s_cselect_b32 s41, s28, s31
	s_cselect_b32 s40, s29, s30
	s_add_i32 s38, 0, 0x14000
	v_add_u32_e32 v76, s35, v157
	v_add_u32_e32 v154, s38, v157
	ds_read_b128 v[60:63], v76
	ds_read_b128 v[68:71], v76 offset:1024
	ds_read_b128 v[72:75], v76 offset:2048
	ds_read_b128 v[76:79], v76 offset:3072
	ds_read_b128 v[170:173], v154
	ds_read_b128 v[174:177], v154 offset:1024
	ds_read_b128 v[178:181], v154 offset:2048
	ds_read_b128 v[182:185], v154 offset:3072
	v_lshl_add_u64 v[154:155], s[74:75], 0, v[150:151]
	s_add_i32 m0, s3, 0xc000
	ds_read_b128 v[186:189], v168
	ds_read_b128 v[190:193], v168 offset:1024
	ds_read_b128 v[194:197], v168 offset:2048
	ds_read_b128 v[198:201], v168 offset:3072
	ds_read_b128 v[202:205], v168 offset:4096
	ds_read_b128 v[206:209], v168 offset:5120
	ds_read_b128 v[214:217], v168 offset:6144
	ds_read_b128 v[218:221], v168 offset:7168
	global_load_lds_dwordx4 v[154:155], off
	v_lshl_add_u64 v[154:155], s[74:75], 0, v[152:153]
	s_add_i32 m0, s3, 0xe000
	s_nop 0
	global_load_lds_dwordx4 v[154:155], off
	s_waitcnt vmcnt(8)
	s_waitcnt lgkmcnt(0)
	s_barrier
	s_setprio 1
	s_waitcnt lgkmcnt(0)
	v_mfma_f32_16x16x32_bf16 v[140:143], v[60:63], v[186:189], v[140:143]
	v_mfma_f32_16x16x32_bf16 v[140:143], v[68:71], v[190:193], v[140:143]
	v_mfma_f32_16x16x32_bf16 v[136:139], v[72:75], v[186:189], v[136:139]
	v_mfma_f32_16x16x32_bf16 v[136:139], v[76:79], v[190:193], v[136:139]
	v_mfma_f32_16x16x32_bf16 v[124:127], v[60:63], v[194:197], v[124:127]
	v_mfma_f32_16x16x32_bf16 v[124:127], v[68:71], v[198:201], v[124:127]
	v_mfma_f32_16x16x32_bf16 v[120:123], v[72:75], v[194:197], v[120:123]
	v_mfma_f32_16x16x32_bf16 v[120:123], v[76:79], v[198:201], v[120:123]
	v_mfma_f32_16x16x32_bf16 v[108:111], v[60:63], v[202:205], v[108:111]
	v_mfma_f32_16x16x32_bf16 v[108:111], v[68:71], v[206:209], v[108:111]
	v_mfma_f32_16x16x32_bf16 v[104:107], v[72:75], v[202:205], v[104:107]
	v_mfma_f32_16x16x32_bf16 v[104:107], v[76:79], v[206:209], v[104:107]
	v_mfma_f32_16x16x32_bf16 v[92:95], v[60:63], v[214:217], v[92:95]
	v_mfma_f32_16x16x32_bf16 v[92:95], v[68:71], v[218:221], v[92:95]
	v_mfma_f32_16x16x32_bf16 v[88:91], v[72:75], v[214:217], v[88:91]
	v_mfma_f32_16x16x32_bf16 v[88:91], v[76:79], v[218:221], v[88:91]
	s_setprio 0
	s_setprio 1
	v_mfma_f32_16x16x32_bf16 v[132:135], v[170:173], v[186:189], v[132:135]
	v_mfma_f32_16x16x32_bf16 v[132:135], v[174:177], v[190:193], v[132:135]
	v_mfma_f32_16x16x32_bf16 v[128:131], v[178:181], v[186:189], v[128:131]
	v_mfma_f32_16x16x32_bf16 v[128:131], v[182:185], v[190:193], v[128:131]
	v_mfma_f32_16x16x32_bf16 v[116:119], v[170:173], v[194:197], v[116:119]
	v_mfma_f32_16x16x32_bf16 v[116:119], v[174:177], v[198:201], v[116:119]
	v_mfma_f32_16x16x32_bf16 v[112:115], v[178:181], v[194:197], v[112:115]
	v_mfma_f32_16x16x32_bf16 v[112:115], v[182:185], v[198:201], v[112:115]
	v_mfma_f32_16x16x32_bf16 v[100:103], v[170:173], v[202:205], v[100:103]
	v_mfma_f32_16x16x32_bf16 v[100:103], v[174:177], v[206:209], v[100:103]
	v_mfma_f32_16x16x32_bf16 v[96:99], v[178:181], v[202:205], v[96:99]
	v_mfma_f32_16x16x32_bf16 v[96:99], v[182:185], v[206:209], v[96:99]
	v_mfma_f32_16x16x32_bf16 v[84:87], v[170:173], v[214:217], v[84:87]
	v_mfma_f32_16x16x32_bf16 v[84:87], v[174:177], v[218:221], v[84:87]
	v_mfma_f32_16x16x32_bf16 v[80:83], v[178:181], v[214:217], v[80:83]
	v_mfma_f32_16x16x32_bf16 v[80:83], v[182:185], v[218:221], v[80:83]
	s_setprio 0
	s_barrier
	s_add_i32 s35, s35, s0
	v_lshl_add_u64 v[154:155], s[40:41], 0, v[212:213]
	s_mov_b32 m0, s35
	ds_read_b128 v[186:189], v168 offset:16384
	ds_read_b128 v[190:193], v168 offset:17408
	ds_read_b128 v[194:197], v168 offset:18432
	ds_read_b128 v[198:201], v168 offset:19456
	ds_read_b128 v[202:205], v168 offset:20480
	ds_read_b128 v[206:209], v168 offset:21504
	ds_read_b128 v[214:217], v168 offset:22528
	ds_read_b128 v[218:221], v168 offset:23552
	global_load_lds_dwordx4 v[154:155], off
	s_add_i32 m0, s35, 0x2000
	s_add_u32 s36, s40, 0x40000
	v_lshl_add_u64 v[210:211], s[40:41], 0, v[148:149]
	s_addc_u32 s37, s41, 0
	s_add_i32 s35, s38, s0
	global_load_lds_dwordx4 v[210:211], off
	v_lshl_add_u64 v[222:223], s[36:37], 0, v[212:213]
	s_mov_b32 m0, s35
	v_lshl_add_u64 v[224:225], s[14:15], 0, v[146:147]
	global_load_lds_dwordx4 v[222:223], off
	v_lshl_add_u64 v[222:223], s[36:37], 0, v[148:149]
	s_add_i32 m0, s35, 0x2000
	s_nop 0
	global_load_lds_dwordx4 v[222:223], off
	v_lshl_add_u64 v[222:223], s[14:15], 0, v[144:145]
	s_mov_b32 m0, s3
	s_nop 0
	global_load_lds_dwordx4 v[222:223], off
	s_mov_b32 m0, s16
	s_nop 0
	global_load_lds_dwordx4 v[224:225], off
	s_waitcnt vmcnt(8)
	s_waitcnt lgkmcnt(0)
	s_barrier
; #define PG8_STAGE(bufoff, gbase, voff) do { _Pragma("unroll") for (int _i = 0; _i < 2; ++_i) \
;         __builtin_amdgcn_global_load_lds((const unsigned*)((const char*)(gbase) + (voff)[_i]), (PG8_LAS unsigned*)(lds + (bufoff) + ldsw + _i * 8192), 16, 0, 0); } while (0)
; #define PG8_LDA(dst, b, h) do { _Pragma("unroll") for (int m = 0; m < 4; ++m) _Pragma("unroll") for (int k = 0; k < 2; ++k) dst[m][k] = *(const PG8_LAS bf16x8*)(lds + PG8_SA(b, h) + aoff + m * 2048 + k * 1024); } while (0)
; #define PG8_LDB(dst, b, h) do { _Pragma("unroll") for (int n = 0; n < 2; ++n) _Pragma("unroll") for (int k = 0; k < 2; ++k) dst[n][k] = *(const PG8_LAS bf16x8*)(lds + PG8_SB(b, h) + boff + n * 2048 + k * 1024); } while (0)
; #define PG8_MMA(ai, bj, At, Bt) do { __builtin_amdgcn_s_setprio(1); _Pragma("unroll") for (int m = 0; m < 4; ++m) _Pragma("unroll") for (int n = 0; n < 2; ++n) _Pragma("unroll") for (int k = 0; k < 2; ++k) \
;         acc[ai][bj][m][n] = __builtin_amdgcn_mfma_f32_16x16x32_bf16(Bt[n][k], At[m][k], acc[ai][bj][m][n], 0, 0, 0); __builtin_amdgcn_s_setprio(0); } while (0)
; #define PG8_WAIT_V(n) asm volatile("s_waitcnt vmcnt(" #n ")" ::: "memory")
; #define PG8_WAIT_L(n) asm volatile("s_waitcnt lgkmcnt(" #n ")" ::: "memory")
; #define PG8_BAR __builtin_amdgcn_s_barrier()
; #define PG8_SCHED __builtin_amdgcn_sched_barrier(0)
; template <class Epi, class Sched, bool ALIGN_EPI = false, bool SP2 = false>
; __device__ __forceinline__ void gemm_phase(PG8_LAS unsigned char* lds, const Gemm g, const Sched& S, const Epi& E) {
;     ...
;             PG8_WAIT_V(8); PG8_WAIT_L(0); PG8_BAR; PG8_MMA(1, 0, At, B0); PG8_MMA(1, 1, At, B1); PG8_BAR; PG8_SCHED;
;             PG8_LDB(B0, 1, 0); PG8_LDB(B1, 1, 1); PG8_SCHED; PG8_LDA(At, 1, 0); PG8_STAGE(PG8_SA(0, 1), a2 + hstepA, voffA);
;             PG8_WAIT_V(8); PG8_WAIT_L(0); PG8_BAR; PG8_MMA(0, 0, At, B0); PG8_MMA(0, 1, At, B1); PG8_BAR; PG8_SCHED;
	s_setprio 1
	s_waitcnt lgkmcnt(0)
	v_mfma_f32_16x16x32_bf16 v[64:67], v[60:63], v[186:189], v[64:67]
	v_mfma_f32_16x16x32_bf16 v[64:67], v[68:71], v[190:193], v[64:67]
	v_mfma_f32_16x16x32_bf16 v[56:59], v[72:75], v[186:189], v[56:59]
	v_mfma_f32_16x16x32_bf16 v[56:59], v[76:79], v[190:193], v[56:59]
	v_mfma_f32_16x16x32_bf16 v[44:47], v[60:63], v[194:197], v[44:47]
	v_mfma_f32_16x16x32_bf16 v[44:47], v[68:71], v[198:201], v[44:47]
	v_mfma_f32_16x16x32_bf16 v[40:43], v[72:75], v[194:197], v[40:43]
	v_mfma_f32_16x16x32_bf16 v[40:43], v[76:79], v[198:201], v[40:43]
	v_mfma_f32_16x16x32_bf16 v[28:31], v[60:63], v[202:205], v[28:31]
	v_mfma_f32_16x16x32_bf16 v[28:31], v[68:71], v[206:209], v[28:31]
	v_mfma_f32_16x16x32_bf16 v[24:27], v[72:75], v[202:205], v[24:27]
	v_mfma_f32_16x16x32_bf16 v[24:27], v[76:79], v[206:209], v[24:27]
	v_mfma_f32_16x16x32_bf16 v[12:15], v[60:63], v[214:217], v[12:15]
	v_mfma_f32_16x16x32_bf16 v[12:15], v[68:71], v[218:221], v[12:15]
	v_mfma_f32_16x16x32_bf16 v[8:11], v[72:75], v[214:217], v[8:11]
	v_mfma_f32_16x16x32_bf16 v[8:11], v[76:79], v[218:221], v[8:11]
	s_setprio 0
	s_setprio 1
	v_mfma_f32_16x16x32_bf16 v[52:55], v[170:173], v[186:189], v[52:55]
	v_mfma_f32_16x16x32_bf16 v[52:55], v[174:177], v[190:193], v[52:55]
	v_mfma_f32_16x16x32_bf16 v[48:51], v[178:181], v[186:189], v[48:51]
	v_mfma_f32_16x16x32_bf16 v[48:51], v[182:185], v[190:193], v[48:51]
	v_mfma_f32_16x16x32_bf16 v[36:39], v[170:173], v[194:197], v[36:39]
	v_mfma_f32_16x16x32_bf16 v[36:39], v[174:177], v[198:201], v[36:39]
	v_mfma_f32_16x16x32_bf16 v[32:35], v[178:181], v[194:197], v[32:35]
	v_mfma_f32_16x16x32_bf16 v[32:35], v[182:185], v[198:201], v[32:35]
	v_mfma_f32_16x16x32_bf16 v[20:23], v[170:173], v[202:205], v[20:23]
	v_mfma_f32_16x16x32_bf16 v[20:23], v[174:177], v[206:209], v[20:23]
	v_mfma_f32_16x16x32_bf16 v[16:19], v[178:181], v[202:205], v[16:19]
	v_mfma_f32_16x16x32_bf16 v[16:19], v[182:185], v[206:209], v[16:19]
	v_mfma_f32_16x16x32_bf16 v[4:7], v[170:173], v[214:217], v[4:7]
	v_mfma_f32_16x16x32_bf16 v[4:7], v[174:177], v[218:221], v[4:7]
	v_mfma_f32_16x16x32_bf16 v[0:3], v[178:181], v[214:217], v[0:3]
	v_mfma_f32_16x16x32_bf16 v[0:3], v[182:185], v[218:221], v[0:3]
	s_setprio 0
	s_barrier
	s_add_i32 s35, 0, 0x18000
	s_add_i32 s36, 0, 0x1c000
	v_add_u32_e32 v76, s35, v157
	v_add_u32_e32 v169, s36, v157
	ds_read_b128 v[60:63], v76
	ds_read_b128 v[68:71], v76 offset:1024
	ds_read_b128 v[72:75], v76 offset:2048
	ds_read_b128 v[76:79], v76 offset:3072
	ds_read_b128 v[170:173], v169
	ds_read_b128 v[174:177], v169 offset:1024
	ds_read_b128 v[178:181], v169 offset:2048
	ds_read_b128 v[182:185], v169 offset:3072
	s_add_u32 s14, s14, 0x40000
	s_addc_u32 s15, s15, 0
	s_mov_b32 m0, s17
	v_lshl_add_u64 v[240:241], s[14:15], 0, v[144:145]
	ds_read_b128 v[186:189], v168 offset:32768
	ds_read_b128 v[190:193], v168 offset:33792
	ds_read_b128 v[194:197], v168 offset:34816
	ds_read_b128 v[198:201], v168 offset:35840
	ds_read_b128 v[202:205], v168 offset:36864
	ds_read_b128 v[206:209], v168 offset:37888
	ds_read_b128 v[214:217], v168 offset:38912
	ds_read_b128 v[218:221], v168 offset:39936
	global_load_lds_dwordx4 v[240:241], off
	v_lshl_add_u64 v[240:241], s[14:15], 0, v[146:147]
	s_mov_b32 m0, s18
	s_nop 0
	global_load_lds_dwordx4 v[240:241], off
	s_waitcnt vmcnt(8)
	s_waitcnt lgkmcnt(0)
	s_barrier
	s_setprio 1
	s_waitcnt lgkmcnt(0)
	v_mfma_f32_16x16x32_bf16 v[140:143], v[60:63], v[186:189], v[140:143]
	v_mfma_f32_16x16x32_bf16 v[140:143], v[68:71], v[190:193], v[140:143]
	v_mfma_f32_16x16x32_bf16 v[136:139], v[72:75], v[186:189], v[136:139]
	v_mfma_f32_16x16x32_bf16 v[136:139], v[76:79], v[190:193], v[136:139]
	v_mfma_f32_16x16x32_bf16 v[124:127], v[60:63], v[194:197], v[124:127]
	v_mfma_f32_16x16x32_bf16 v[124:127], v[68:71], v[198:201], v[124:127]
	v_mfma_f32_16x16x32_bf16 v[120:123], v[72:75], v[194:197], v[120:123]
	v_mfma_f32_16x16x32_bf16 v[120:123], v[76:79], v[198:201], v[120:123]
	v_mfma_f32_16x16x32_bf16 v[108:111], v[60:63], v[202:205], v[108:111]
	v_mfma_f32_16x16x32_bf16 v[108:111], v[68:71], v[206:209], v[108:111]
	v_mfma_f32_16x16x32_bf16 v[104:107], v[72:75], v[202:205], v[104:107]
	v_mfma_f32_16x16x32_bf16 v[104:107], v[76:79], v[206:209], v[104:107]
	v_mfma_f32_16x16x32_bf16 v[92:95], v[60:63], v[214:217], v[92:95]
	v_mfma_f32_16x16x32_bf16 v[92:95], v[68:71], v[218:221], v[92:95]
	v_mfma_f32_16x16x32_bf16 v[88:91], v[72:75], v[214:217], v[88:91]
	v_mfma_f32_16x16x32_bf16 v[88:91], v[76:79], v[218:221], v[88:91]
	s_setprio 0
	s_setprio 1
	v_mfma_f32_16x16x32_bf16 v[132:135], v[170:173], v[186:189], v[132:135]
	v_mfma_f32_16x16x32_bf16 v[132:135], v[174:177], v[190:193], v[132:135]
	v_mfma_f32_16x16x32_bf16 v[128:131], v[178:181], v[186:189], v[128:131]
	v_mfma_f32_16x16x32_bf16 v[128:131], v[182:185], v[190:193], v[128:131]
	v_mfma_f32_16x16x32_bf16 v[116:119], v[170:173], v[194:197], v[116:119]
	v_mfma_f32_16x16x32_bf16 v[116:119], v[174:177], v[198:201], v[116:119]
	v_mfma_f32_16x16x32_bf16 v[112:115], v[178:181], v[194:197], v[112:115]
	v_mfma_f32_16x16x32_bf16 v[112:115], v[182:185], v[198:201], v[112:115]
	v_mfma_f32_16x16x32_bf16 v[100:103], v[170:173], v[202:205], v[100:103]
	v_mfma_f32_16x16x32_bf16 v[100:103], v[174:177], v[206:209], v[100:103]
	v_mfma_f32_16x16x32_bf16 v[96:99], v[178:181], v[202:205], v[96:99]
	v_mfma_f32_16x16x32_bf16 v[96:99], v[182:185], v[206:209], v[96:99]
	v_mfma_f32_16x16x32_bf16 v[84:87], v[170:173], v[214:217], v[84:87]
	v_mfma_f32_16x16x32_bf16 v[84:87], v[174:177], v[218:221], v[84:87]
	v_mfma_f32_16x16x32_bf16 v[80:83], v[178:181], v[214:217], v[80:83]
	v_mfma_f32_16x16x32_bf16 v[80:83], v[182:185], v[218:221], v[80:83]
	s_setprio 0
	s_barrier
; #define PG8_STAGE(bufoff, gbase, voff) do { _Pragma("unroll") for (int _i = 0; _i < 2; ++_i) \
;         __builtin_amdgcn_global_load_lds((const unsigned*)((const char*)(gbase) + (voff)[_i]), (PG8_LAS unsigned*)(lds + (bufoff) + ldsw + _i * 8192), 16, 0, 0); } while (0)
; #define PG8_LDA(dst, b, h) do { _Pragma("unroll") for (int m = 0; m < 4; ++m) _Pragma("unroll") for (int k = 0; k < 2; ++k) dst[m][k] = *(const PG8_LAS bf16x8*)(lds + PG8_SA(b, h) + aoff + m * 2048 + k * 1024); } while (0)
; #define PG8_MMA(ai, bj, At, Bt) do { __builtin_amdgcn_s_setprio(1); _Pragma("unroll") for (int m = 0; m < 4; ++m) _Pragma("unroll") for (int n = 0; n < 2; ++n) _Pragma("unroll") for (int k = 0; k < 2; ++k) \
;         acc[ai][bj][m][n] = __builtin_amdgcn_mfma_f32_16x16x32_bf16(Bt[n][k], At[m][k], acc[ai][bj][m][n], 0, 0, 0); __builtin_amdgcn_s_setprio(0); } while (0)
; #define PG8_WAIT_V(n) asm volatile("s_waitcnt vmcnt(" #n ")" ::: "memory")
; #define PG8_WAIT_L(n) asm volatile("s_waitcnt lgkmcnt(" #n ")" ::: "memory")
; #define PG8_BAR __builtin_amdgcn_s_barrier()
; #define PG8_SCHED __builtin_amdgcn_sched_barrier(0)
; template <class Epi, class Sched, bool ALIGN_EPI = false, bool SP2 = false>
; __device__ __forceinline__ void gemm_phase(PG8_LAS unsigned char* lds, const Gemm g, const Sched& S, const Epi& E) {
;     ...
;         for (int t = 0; t < nt; t += 2) {
;     ...
;             PG8_LDA(At, 1, 1); PG8_STAGE(PG8_SB(1, 0), b3, voffB); PG8_STAGE(PG8_SB(1, 1), b3 + hstep, voffB); PG8_STAGE(PG8_SA(1, 0), a3, voffA);
;             PG8_WAIT_V(8); PG8_WAIT_L(0); PG8_BAR; PG8_MMA(1, 0, At, B0); PG8_MMA(1, 1, At, B1); PG8_BAR; PG8_SCHED;
;     ...
;         if constexpr (ALIGN_EPI) { if (wr == 0) PG8_BAR; }
	s_add_i32 s14, s35, s0
	v_lshl_add_u64 v[154:155], v[154:155], 0, s[22:23]
	s_mov_b32 m0, s14
	ds_read_b128 v[186:189], v168 offset:49152
	ds_read_b128 v[190:193], v168 offset:50176
	ds_read_b128 v[194:197], v168 offset:51200
	ds_read_b128 v[198:201], v168 offset:52224
	ds_read_b128 v[202:205], v168 offset:53248
	ds_read_b128 v[206:209], v168 offset:54272
	ds_read_b128 v[214:217], v168 offset:55296
	ds_read_b128 v[218:221], v168 offset:56320
	global_load_lds_dwordx4 v[154:155], off
	s_add_i32 m0, s14, 0x2000
	s_add_u32 s14, s40, 0x40080
	v_lshl_add_u64 v[154:155], v[210:211], 0, s[22:23]
	s_addc_u32 s15, s41, 0
	s_add_i32 s35, s36, s0
	global_load_lds_dwordx4 v[154:155], off
	v_lshl_add_u64 v[154:155], s[14:15], 0, v[212:213]
	s_mov_b32 m0, s35
	s_nop 0
	global_load_lds_dwordx4 v[154:155], off
	v_lshl_add_u64 v[154:155], s[14:15], 0, v[148:149]
	s_add_i32 m0, s35, 0x2000
	s_nop 0
	global_load_lds_dwordx4 v[154:155], off
	v_lshl_add_u64 v[154:155], v[222:223], 0, s[22:23]
	s_mov_b32 m0, s20
	s_nop 0
	global_load_lds_dwordx4 v[154:155], off
	v_lshl_add_u64 v[154:155], v[224:225], 0, s[22:23]
	s_mov_b32 m0, s21
	s_nop 0
	global_load_lds_dwordx4 v[154:155], off
	s_waitcnt vmcnt(8)
	s_waitcnt lgkmcnt(0)
	s_barrier
	s_setprio 1
	s_waitcnt lgkmcnt(0)
	v_mfma_f32_16x16x32_bf16 v[64:67], v[60:63], v[186:189], v[64:67]
	v_mfma_f32_16x16x32_bf16 v[64:67], v[68:71], v[190:193], v[64:67]
	v_mfma_f32_16x16x32_bf16 v[56:59], v[72:75], v[186:189], v[56:59]
	v_mfma_f32_16x16x32_bf16 v[56:59], v[76:79], v[190:193], v[56:59]
	v_mfma_f32_16x16x32_bf16 v[44:47], v[60:63], v[194:197], v[44:47]
	v_mfma_f32_16x16x32_bf16 v[44:47], v[68:71], v[198:201], v[44:47]
	v_mfma_f32_16x16x32_bf16 v[40:43], v[72:75], v[194:197], v[40:43]
	v_mfma_f32_16x16x32_bf16 v[40:43], v[76:79], v[198:201], v[40:43]
	v_mfma_f32_16x16x32_bf16 v[28:31], v[60:63], v[202:205], v[28:31]
	v_mfma_f32_16x16x32_bf16 v[28:31], v[68:71], v[206:209], v[28:31]
	v_mfma_f32_16x16x32_bf16 v[24:27], v[72:75], v[202:205], v[24:27]
	v_mfma_f32_16x16x32_bf16 v[24:27], v[76:79], v[206:209], v[24:27]
	v_mfma_f32_16x16x32_bf16 v[12:15], v[60:63], v[214:217], v[12:15]
	v_mfma_f32_16x16x32_bf16 v[12:15], v[68:71], v[218:221], v[12:15]
	v_mfma_f32_16x16x32_bf16 v[8:11], v[72:75], v[214:217], v[8:11]
	v_mfma_f32_16x16x32_bf16 v[8:11], v[76:79], v[218:221], v[8:11]
	s_setprio 0
	s_setprio 1
	v_mfma_f32_16x16x32_bf16 v[52:55], v[170:173], v[186:189], v[52:55]
	v_mfma_f32_16x16x32_bf16 v[52:55], v[174:177], v[190:193], v[52:55]
	v_mfma_f32_16x16x32_bf16 v[48:51], v[178:181], v[186:189], v[48:51]
	v_mfma_f32_16x16x32_bf16 v[48:51], v[182:185], v[190:193], v[48:51]
	v_mfma_f32_16x16x32_bf16 v[36:39], v[170:173], v[194:197], v[36:39]
	v_mfma_f32_16x16x32_bf16 v[36:39], v[174:177], v[198:201], v[36:39]
	v_mfma_f32_16x16x32_bf16 v[32:35], v[178:181], v[194:197], v[32:35]
	v_mfma_f32_16x16x32_bf16 v[32:35], v[182:185], v[198:201], v[32:35]
	v_mfma_f32_16x16x32_bf16 v[20:23], v[170:173], v[202:205], v[20:23]
	v_mfma_f32_16x16x32_bf16 v[20:23], v[174:177], v[206:209], v[20:23]
	v_mfma_f32_16x16x32_bf16 v[16:19], v[178:181], v[202:205], v[16:19]
	v_mfma_f32_16x16x32_bf16 v[16:19], v[182:185], v[206:209], v[16:19]
	v_mfma_f32_16x16x32_bf16 v[4:7], v[170:173], v[214:217], v[4:7]
	v_mfma_f32_16x16x32_bf16 v[4:7], v[174:177], v[218:221], v[4:7]
	v_mfma_f32_16x16x32_bf16 v[0:3], v[178:181], v[214:217], v[0:3]
	v_mfma_f32_16x16x32_bf16 v[0:3], v[182:185], v[218:221], v[0:3]
	s_setprio 0
	s_barrier
	s_add_i32 s34, s34, 2
	s_add_u32 s74, s74, 0x100
	s_addc_u32 s75, s75, 0
	s_add_u32 s30, s30, 0x100
	s_addc_u32 s31, s31, 0
	s_cmp_gt_u32 s34, 13
	s_cbranch_scc0 .LBB0_119
	s_and_b64 vcc, exec, s[62:63]
	s_cbranch_vccz .LBB0_122
	s_barrier

; #define PG8_STAGE(bufoff, gbase, voff) do { _Pragma("unroll") for (int _i = 0; _i < 2; ++_i) \
;         __builtin_amdgcn_global_load_lds((const unsigned*)((const char*)(gbase) + (voff)[_i]), (PG8_LAS unsigned*)(lds + (bufoff) + ldsw + _i * 8192), 16, 0, 0); } while (0)
; #define PG8_LDA(dst, b, h) do { _Pragma("unroll") for (int m = 0; m < 4; ++m) _Pragma("unroll") for (int k = 0; k < 2; ++k) dst[m][k] = *(const PG8_LAS bf16x8*)(lds + PG8_SA(b, h) + aoff + m * 2048 + k * 1024); } while (0)
; #define PG8_LDB(dst, b, h) do { _Pragma("unroll") for (int n = 0; n < 2; ++n) _Pragma("unroll") for (int k = 0; k < 2; ++k) dst[n][k] = *(const PG8_LAS bf16x8*)(lds + PG8_SB(b, h) + boff + n * 2048 + k * 1024); } while (0)
; #define PG8_WAIT_V(n) asm volatile("s_waitcnt vmcnt(" #n ")" ::: "memory")
; #define PG8_WAIT_L(n) asm volatile("s_waitcnt lgkmcnt(" #n ")" ::: "memory")
; #define PG8_BAR __builtin_amdgcn_s_barrier()
; #define PG8_SCHED __builtin_amdgcn_sched_barrier(0)
; template <class Epi, class Sched, bool ALIGN_EPI = false, bool SP2 = false>
; __device__ __forceinline__ void gemm_phase(PG8_LAS unsigned char* lds, const Gemm g, const Sched& S, const Epi& E) {
;     ...
;             const char* a1 = cA + (g.gstrA ? (size_t)(t >> 2) * g.gstrA + (size_t)(t & 3) * kstep : (size_t)t * kstep) + kstep;
;             const char* a2 = last ? nA : cA + (g.gstrA ? (size_t)((t + 2) >> 2) * g.gstrA + (size_t)((t + 2) & 3) * kstep : (size_t)(t + 2) * kstep); const char* b2 = last ? nB : cB + (size_t)(t + 2) * kstep;
;             const char* a3 = a2 + kstep; const char* b3 = b2 + kstep;
;             if (last && has_next) S.a_ready(nxt);
;             if constexpr (Epi::HAS_PREFETCH) { if (t == nt - 4) E.prefetch(cur, tid, wid); }
;             if constexpr (SP2) {
;             PG8_LDB(B0, 0, 0); PG8_LDB(B1, 0, 1); PG8_SCHED; PG8_LDA(At, 0, 0); PG8_STAGE(PG8_SA(1, 1), a1 + hstepA, voffA);
;             PG8_WAIT_V(8); PG8_WAIT_L(0); PG8_BAR; PG8_MMA(0, 0, At, B0); PG8_MMA(0, 1, At, B1); PG8_BAR; PG8_SCHED;
;             PG8_LDA(At, 0, 1); PG8_STAGE(PG8_SB(0, 0), b2, voffB); PG8_STAGE(PG8_SB(0, 1), b2 + hstep, voffB); PG8_STAGE(PG8_SA(0, 0), a2, voffA);
;             PG8_WAIT_V(8); PG8_WAIT_L(0); PG8_BAR; PG8_MMA(1, 0, At, B0); PG8_MMA(1, 1, At, B1); PG8_BAR; PG8_SCHED;
.LBB0_183:
	s_add_u32 vcc_lo, s30, s40
	s_addc_u32 vcc_hi, s34, s41
	s_add_i32 s38, 0, 0x10000
	s_and_b64 s[12:13], exec, s[14:15]
	s_cselect_b32 s13, s91, vcc_hi
	s_cselect_b32 s12, s90, vcc_lo
	s_add_i32 vcc_lo, 0, 0x14000
	v_add_u32_e32 v140, s38, v240
	v_add_u32_e32 v156, vcc_lo, v240
	ds_read_b128 v[128:131], v140
	ds_read_b128 v[132:135], v140 offset:1024
	ds_read_b128 v[136:139], v140 offset:2048
	ds_read_b128 v[140:143], v140 offset:3072
	ds_read_b128 v[144:147], v156
	ds_read_b128 v[148:151], v156 offset:1024
	ds_read_b128 v[152:155], v156 offset:2048
	ds_read_b128 v[156:159], v156 offset:3072
	s_add_u32 s14, s24, s94
	s_addc_u32 s15, s26, s95
	v_lshl_add_u64 v[198:199], s[14:15], 0, v[192:193]
	v_lshl_add_u64 v[198:199], v[198:199], 0, s[22:23]
	s_add_i32 m0, s52, 0xc000
	ds_read_b128 v[160:163], v243
	ds_read_b128 v[164:167], v243 offset:1024
	ds_read_b128 v[168:171], v243 offset:2048
	ds_read_b128 v[172:175], v243 offset:3072
	ds_read_b128 v[176:179], v243 offset:4096
	ds_read_b128 v[180:183], v243 offset:5120
	ds_read_b128 v[184:187], v243 offset:6144
	ds_read_b128 v[188:191], v243 offset:7168
	global_load_lds_dwordx4 v[198:199], off
	v_lshl_add_u64 v[198:199], s[14:15], 0, v[194:195]
	v_lshl_add_u64 v[198:199], v[198:199], 0, s[22:23]
	s_add_i32 m0, s52, 0xe000
	s_nop 0
	global_load_lds_dwordx4 v[198:199], off
	s_waitcnt vmcnt(8)
	s_waitcnt lgkmcnt(0)
	s_barrier
	s_setprio 1
	s_waitcnt lgkmcnt(0)
	v_mfma_f32_16x16x32_bf16 v[124:127], v[128:131], v[160:163], v[124:127]
	v_mfma_f32_16x16x32_bf16 v[124:127], v[132:135], v[164:167], v[124:127]
	v_mfma_f32_16x16x32_bf16 v[120:123], v[136:139], v[160:163], v[120:123]
	v_mfma_f32_16x16x32_bf16 v[120:123], v[140:143], v[164:167], v[120:123]
	v_mfma_f32_16x16x32_bf16 v[108:111], v[128:131], v[168:171], v[108:111]
	v_mfma_f32_16x16x32_bf16 v[108:111], v[132:135], v[172:175], v[108:111]
	v_mfma_f32_16x16x32_bf16 v[104:107], v[136:139], v[168:171], v[104:107]
	v_mfma_f32_16x16x32_bf16 v[104:107], v[140:143], v[172:175], v[104:107]
	v_mfma_f32_16x16x32_bf16 v[92:95], v[128:131], v[176:179], v[92:95]
	v_mfma_f32_16x16x32_bf16 v[92:95], v[132:135], v[180:183], v[92:95]
	v_mfma_f32_16x16x32_bf16 v[88:91], v[136:139], v[176:179], v[88:91]
	v_mfma_f32_16x16x32_bf16 v[88:91], v[140:143], v[180:183], v[88:91]
	v_mfma_f32_16x16x32_bf16 v[76:79], v[128:131], v[184:187], v[76:79]
	v_mfma_f32_16x16x32_bf16 v[76:79], v[132:135], v[188:191], v[76:79]
	v_mfma_f32_16x16x32_bf16 v[72:75], v[136:139], v[184:187], v[72:75]
	v_mfma_f32_16x16x32_bf16 v[72:75], v[140:143], v[188:191], v[72:75]
	s_setprio 0
	s_setprio 1
	v_mfma_f32_16x16x32_bf16 v[116:119], v[144:147], v[160:163], v[116:119]
	v_mfma_f32_16x16x32_bf16 v[116:119], v[148:151], v[164:167], v[116:119]
	v_mfma_f32_16x16x32_bf16 v[112:115], v[152:155], v[160:163], v[112:115]
	v_mfma_f32_16x16x32_bf16 v[112:115], v[156:159], v[164:167], v[112:115]
	v_mfma_f32_16x16x32_bf16 v[100:103], v[144:147], v[168:171], v[100:103]
	v_mfma_f32_16x16x32_bf16 v[100:103], v[148:151], v[172:175], v[100:103]
	v_mfma_f32_16x16x32_bf16 v[96:99], v[152:155], v[168:171], v[96:99]
	v_mfma_f32_16x16x32_bf16 v[96:99], v[156:159], v[172:175], v[96:99]
	v_mfma_f32_16x16x32_bf16 v[84:87], v[144:147], v[176:179], v[84:87]
	v_mfma_f32_16x16x32_bf16 v[84:87], v[148:151], v[180:183], v[84:87]
	v_mfma_f32_16x16x32_bf16 v[80:83], v[152:155], v[176:179], v[80:83]
	v_mfma_f32_16x16x32_bf16 v[80:83], v[156:159], v[180:183], v[80:83]
	v_mfma_f32_16x16x32_bf16 v[68:71], v[144:147], v[184:187], v[68:71]
	v_mfma_f32_16x16x32_bf16 v[68:71], v[148:151], v[188:191], v[68:71]
	v_mfma_f32_16x16x32_bf16 v[64:67], v[152:155], v[184:187], v[64:67]
	v_mfma_f32_16x16x32_bf16 v[64:67], v[156:159], v[188:191], v[64:67]
	s_setprio 0
	s_barrier
	s_add_i32 s14, s38, s55
	v_lshl_add_u64 v[198:199], s[12:13], 0, v[212:213]
	s_mov_b32 m0, s14
	ds_read_b128 v[160:163], v243 offset:16384
	ds_read_b128 v[164:167], v243 offset:17408
	ds_read_b128 v[168:171], v243 offset:18432
	ds_read_b128 v[172:175], v243 offset:19456
	ds_read_b128 v[176:179], v243 offset:20480
	ds_read_b128 v[180:183], v243 offset:21504
	ds_read_b128 v[184:187], v243 offset:22528
	ds_read_b128 v[188:191], v243 offset:23552
	global_load_lds_dwordx4 v[198:199], off
	s_add_i32 m0, s14, 0x2000
	v_lshl_add_u64 v[200:201], s[12:13], 0, v[196:197]
	s_add_u32 s12, s12, s25
	s_addc_u32 s13, s13, 0
	s_add_i32 s14, vcc_lo, s55
	global_load_lds_dwordx4 v[200:201], off
	v_lshl_add_u64 v[202:203], s[12:13], 0, v[212:213]
	s_mov_b32 m0, s14
	v_lshl_add_u64 v[204:205], s[12:13], 0, v[196:197]
	global_load_lds_dwordx4 v[202:203], off
	s_add_i32 m0, s14, 0x2000
	v_lshl_add_u64 v[206:207], s[96:97], 0, v[192:193]
	global_load_lds_dwordx4 v[204:205], off
	s_mov_b32 m0, s52
	v_lshl_add_u64 v[208:209], s[96:97], 0, v[194:195]
	global_load_lds_dwordx4 v[206:207], off
	s_mov_b32 m0, s31
	s_nop 0
	global_load_lds_dwordx4 v[208:209], off
	s_waitcnt vmcnt(8)
	s_waitcnt lgkmcnt(0)
	s_barrier
; #define PG8_STAGE(bufoff, gbase, voff) do { _Pragma("unroll") for (int _i = 0; _i < 2; ++_i) \
;         __builtin_amdgcn_global_load_lds((const unsigned*)((const char*)(gbase) + (voff)[_i]), (PG8_LAS unsigned*)(lds + (bufoff) + ldsw + _i * 8192), 16, 0, 0); } while (0)
; #define PG8_LDA(dst, b, h) do { _Pragma("unroll") for (int m = 0; m < 4; ++m) _Pragma("unroll") for (int k = 0; k < 2; ++k) dst[m][k] = *(const PG8_LAS bf16x8*)(lds + PG8_SA(b, h) + aoff + m * 2048 + k * 1024); } while (0)
; #define PG8_LDB(dst, b, h) do { _Pragma("unroll") for (int n = 0; n < 2; ++n) _Pragma("unroll") for (int k = 0; k < 2; ++k) dst[n][k] = *(const PG8_LAS bf16x8*)(lds + PG8_SB(b, h) + boff + n * 2048 + k * 1024); } while (0)
; #define PG8_MMA(ai, bj, At, Bt) do { __builtin_amdgcn_s_setprio(1); _Pragma("unroll") for (int m = 0; m < 4; ++m) _Pragma("unroll") for (int n = 0; n < 2; ++n) _Pragma("unroll") for (int k = 0; k < 2; ++k) \
;         acc[ai][bj][m][n] = __builtin_amdgcn_mfma_f32_16x16x32_bf16(Bt[n][k], At[m][k], acc[ai][bj][m][n], 0, 0, 0); __builtin_amdgcn_s_setprio(0); } while (0)
; #define PG8_WAIT_V(n) asm volatile("s_waitcnt vmcnt(" #n ")" ::: "memory")
; #define PG8_WAIT_L(n) asm volatile("s_waitcnt lgkmcnt(" #n ")" ::: "memory")
; #define PG8_BAR __builtin_amdgcn_s_barrier()
; #define PG8_SCHED __builtin_amdgcn_sched_barrier(0)
; template <class Epi, class Sched, bool ALIGN_EPI = false, bool SP2 = false>
; __device__ __forceinline__ void gemm_phase(PG8_LAS unsigned char* lds, const Gemm g, const Sched& S, const Epi& E) {
;     ...
;             PG8_WAIT_V(8); PG8_WAIT_L(0); PG8_BAR; PG8_MMA(1, 0, At, B0); PG8_MMA(1, 1, At, B1); PG8_BAR; PG8_SCHED;
;             PG8_LDB(B0, 1, 0); PG8_LDB(B1, 1, 1); PG8_SCHED; PG8_LDA(At, 1, 0); PG8_STAGE(PG8_SA(0, 1), a2 + hstepA, voffA);
;             PG8_WAIT_V(8); PG8_WAIT_L(0); PG8_BAR; PG8_MMA(0, 0, At, B0); PG8_MMA(0, 1, At, B1); PG8_BAR; PG8_SCHED;
	s_setprio 1
	s_waitcnt lgkmcnt(0)
	v_mfma_f32_16x16x32_bf16 v[60:63], v[128:131], v[160:163], v[60:63]
	v_mfma_f32_16x16x32_bf16 v[60:63], v[132:135], v[164:167], v[60:63]
	v_mfma_f32_16x16x32_bf16 v[56:59], v[136:139], v[160:163], v[56:59]
	v_mfma_f32_16x16x32_bf16 v[56:59], v[140:143], v[164:167], v[56:59]
	v_mfma_f32_16x16x32_bf16 v[44:47], v[128:131], v[168:171], v[44:47]
	v_mfma_f32_16x16x32_bf16 v[44:47], v[132:135], v[172:175], v[44:47]
	v_mfma_f32_16x16x32_bf16 v[40:43], v[136:139], v[168:171], v[40:43]
	v_mfma_f32_16x16x32_bf16 v[40:43], v[140:143], v[172:175], v[40:43]
	v_mfma_f32_16x16x32_bf16 v[28:31], v[128:131], v[176:179], v[28:31]
	v_mfma_f32_16x16x32_bf16 v[28:31], v[132:135], v[180:183], v[28:31]
	v_mfma_f32_16x16x32_bf16 v[24:27], v[136:139], v[176:179], v[24:27]
	v_mfma_f32_16x16x32_bf16 v[24:27], v[140:143], v[180:183], v[24:27]
	v_mfma_f32_16x16x32_bf16 v[12:15], v[128:131], v[184:187], v[12:15]
	v_mfma_f32_16x16x32_bf16 v[12:15], v[132:135], v[188:191], v[12:15]
	v_mfma_f32_16x16x32_bf16 v[8:11], v[136:139], v[184:187], v[8:11]
	v_mfma_f32_16x16x32_bf16 v[8:11], v[140:143], v[188:191], v[8:11]
	s_setprio 0
	s_setprio 1
	v_mfma_f32_16x16x32_bf16 v[52:55], v[144:147], v[160:163], v[52:55]
	v_mfma_f32_16x16x32_bf16 v[52:55], v[148:151], v[164:167], v[52:55]
	v_mfma_f32_16x16x32_bf16 v[48:51], v[152:155], v[160:163], v[48:51]
	v_mfma_f32_16x16x32_bf16 v[48:51], v[156:159], v[164:167], v[48:51]
	v_mfma_f32_16x16x32_bf16 v[36:39], v[144:147], v[168:171], v[36:39]
	v_mfma_f32_16x16x32_bf16 v[36:39], v[148:151], v[172:175], v[36:39]
	v_mfma_f32_16x16x32_bf16 v[32:35], v[152:155], v[168:171], v[32:35]
	v_mfma_f32_16x16x32_bf16 v[32:35], v[156:159], v[172:175], v[32:35]
	v_mfma_f32_16x16x32_bf16 v[20:23], v[144:147], v[176:179], v[20:23]
	v_mfma_f32_16x16x32_bf16 v[20:23], v[148:151], v[180:183], v[20:23]
	v_mfma_f32_16x16x32_bf16 v[16:19], v[152:155], v[176:179], v[16:19]
	v_mfma_f32_16x16x32_bf16 v[16:19], v[156:159], v[180:183], v[16:19]
	v_mfma_f32_16x16x32_bf16 v[4:7], v[144:147], v[184:187], v[4:7]
	v_mfma_f32_16x16x32_bf16 v[4:7], v[148:151], v[188:191], v[4:7]
	v_mfma_f32_16x16x32_bf16 v[0:3], v[152:155], v[184:187], v[0:3]
	v_mfma_f32_16x16x32_bf16 v[0:3], v[156:159], v[188:191], v[0:3]
	s_setprio 0
	s_barrier
	s_add_i32 s14, 0, 0x18000
	s_add_i32 s15, 0, 0x1c000
	v_add_u32_e32 v140, s14, v240
	v_add_u32_e32 v156, s15, v240
	ds_read_b128 v[128:131], v140
	ds_read_b128 v[132:135], v140 offset:1024
	ds_read_b128 v[136:139], v140 offset:2048
	ds_read_b128 v[140:143], v140 offset:3072
	ds_read_b128 v[144:147], v156
	ds_read_b128 v[148:151], v156 offset:1024
	ds_read_b128 v[152:155], v156 offset:2048
	ds_read_b128 v[156:159], v156 offset:3072
	s_add_u32 s12, s96, s21
	s_addc_u32 s13, s97, s20
	s_mov_b32 m0, s35
	v_lshl_add_u64 v[210:211], s[12:13], 0, v[192:193]
	ds_read_b128 v[160:163], v243 offset:32768
	ds_read_b128 v[164:167], v243 offset:33792
	ds_read_b128 v[168:171], v243 offset:34816
	ds_read_b128 v[172:175], v243 offset:35840
	ds_read_b128 v[176:179], v243 offset:36864
	ds_read_b128 v[180:183], v243 offset:37888
	ds_read_b128 v[184:187], v243 offset:38912
	ds_read_b128 v[188:191], v243 offset:39936
	global_load_lds_dwordx4 v[210:211], off
	v_lshl_add_u64 v[210:211], s[12:13], 0, v[194:195]
	s_mov_b32 m0, s56
	s_nop 0
	global_load_lds_dwordx4 v[210:211], off
	s_waitcnt vmcnt(8)
	s_waitcnt lgkmcnt(0)
	s_barrier
	s_setprio 1
	s_waitcnt lgkmcnt(0)
	v_mfma_f32_16x16x32_bf16 v[124:127], v[128:131], v[160:163], v[124:127]
	v_mfma_f32_16x16x32_bf16 v[124:127], v[132:135], v[164:167], v[124:127]
	v_mfma_f32_16x16x32_bf16 v[120:123], v[136:139], v[160:163], v[120:123]
	v_mfma_f32_16x16x32_bf16 v[120:123], v[140:143], v[164:167], v[120:123]
	v_mfma_f32_16x16x32_bf16 v[108:111], v[128:131], v[168:171], v[108:111]
	v_mfma_f32_16x16x32_bf16 v[108:111], v[132:135], v[172:175], v[108:111]
	v_mfma_f32_16x16x32_bf16 v[104:107], v[136:139], v[168:171], v[104:107]
	v_mfma_f32_16x16x32_bf16 v[104:107], v[140:143], v[172:175], v[104:107]
	v_mfma_f32_16x16x32_bf16 v[92:95], v[128:131], v[176:179], v[92:95]
	v_mfma_f32_16x16x32_bf16 v[92:95], v[132:135], v[180:183], v[92:95]
	v_mfma_f32_16x16x32_bf16 v[88:91], v[136:139], v[176:179], v[88:91]
	v_mfma_f32_16x16x32_bf16 v[88:91], v[140:143], v[180:183], v[88:91]
	v_mfma_f32_16x16x32_bf16 v[76:79], v[128:131], v[184:187], v[76:79]
	v_mfma_f32_16x16x32_bf16 v[76:79], v[132:135], v[188:191], v[76:79]
	v_mfma_f32_16x16x32_bf16 v[72:75], v[136:139], v[184:187], v[72:75]
	v_mfma_f32_16x16x32_bf16 v[72:75], v[140:143], v[188:191], v[72:75]
	s_setprio 0
	s_setprio 1
	v_mfma_f32_16x16x32_bf16 v[116:119], v[144:147], v[160:163], v[116:119]
	v_mfma_f32_16x16x32_bf16 v[116:119], v[148:151], v[164:167], v[116:119]
	v_mfma_f32_16x16x32_bf16 v[112:115], v[152:155], v[160:163], v[112:115]
	v_mfma_f32_16x16x32_bf16 v[112:115], v[156:159], v[164:167], v[112:115]
	v_mfma_f32_16x16x32_bf16 v[100:103], v[144:147], v[168:171], v[100:103]
	v_mfma_f32_16x16x32_bf16 v[100:103], v[148:151], v[172:175], v[100:103]
	v_mfma_f32_16x16x32_bf16 v[96:99], v[152:155], v[168:171], v[96:99]
	v_mfma_f32_16x16x32_bf16 v[96:99], v[156:159], v[172:175], v[96:99]
	v_mfma_f32_16x16x32_bf16 v[84:87], v[144:147], v[176:179], v[84:87]
	v_mfma_f32_16x16x32_bf16 v[84:87], v[148:151], v[180:183], v[84:87]
	v_mfma_f32_16x16x32_bf16 v[80:83], v[152:155], v[176:179], v[80:83]
	v_mfma_f32_16x16x32_bf16 v[80:83], v[156:159], v[180:183], v[80:83]
	v_mfma_f32_16x16x32_bf16 v[68:71], v[144:147], v[184:187], v[68:71]
	v_mfma_f32_16x16x32_bf16 v[68:71], v[148:151], v[188:191], v[68:71]
	v_mfma_f32_16x16x32_bf16 v[64:67], v[152:155], v[184:187], v[64:67]
	v_mfma_f32_16x16x32_bf16 v[64:67], v[156:159], v[188:191], v[64:67]
	s_setprio 0
	s_barrier
; #define PG8_STAGE(bufoff, gbase, voff) do { _Pragma("unroll") for (int _i = 0; _i < 2; ++_i) \
;         __builtin_amdgcn_global_load_lds((const unsigned*)((const char*)(gbase) + (voff)[_i]), (PG8_LAS unsigned*)(lds + (bufoff) + ldsw + _i * 8192), 16, 0, 0); } while (0)
; #define PG8_LDA(dst, b, h) do { _Pragma("unroll") for (int m = 0; m < 4; ++m) _Pragma("unroll") for (int k = 0; k < 2; ++k) dst[m][k] = *(const PG8_LAS bf16x8*)(lds + PG8_SA(b, h) + aoff + m * 2048 + k * 1024); } while (0)
; #define PG8_MMA(ai, bj, At, Bt) do { __builtin_amdgcn_s_setprio(1); _Pragma("unroll") for (int m = 0; m < 4; ++m) _Pragma("unroll") for (int n = 0; n < 2; ++n) _Pragma("unroll") for (int k = 0; k < 2; ++k) \
;         acc[ai][bj][m][n] = __builtin_amdgcn_mfma_f32_16x16x32_bf16(Bt[n][k], At[m][k], acc[ai][bj][m][n], 0, 0, 0); __builtin_amdgcn_s_setprio(0); } while (0)
; #define PG8_WAIT_V(n) asm volatile("s_waitcnt vmcnt(" #n ")" ::: "memory")
; #define PG8_WAIT_L(n) asm volatile("s_waitcnt lgkmcnt(" #n ")" ::: "memory")
; #define PG8_BAR __builtin_amdgcn_s_barrier()
; #define PG8_SCHED __builtin_amdgcn_sched_barrier(0)
; template <class Epi, class Sched, bool ALIGN_EPI = false, bool SP2 = false>
; __device__ __forceinline__ void gemm_phase(PG8_LAS unsigned char* lds, const Gemm g, const Sched& S, const Epi& E) {
;     ...
;         for (int t = 0; t < nt; t += 2) {
;     ...
;             PG8_LDA(At, 1, 1); PG8_STAGE(PG8_SB(1, 0), b3, voffB); PG8_STAGE(PG8_SB(1, 1), b3 + hstep, voffB); PG8_STAGE(PG8_SA(1, 0), a3, voffA);
;             PG8_WAIT_V(8); PG8_WAIT_L(0); PG8_BAR; PG8_MMA(1, 0, At, B0); PG8_MMA(1, 1, At, B1); PG8_BAR; PG8_SCHED;
	s_add_i32 s12, s14, s55
	v_lshl_add_u64 v[198:199], v[198:199], 0, s[22:23]
	s_mov_b32 m0, s12
	ds_read_b128 v[160:163], v243 offset:49152
	ds_read_b128 v[164:167], v243 offset:50176
	ds_read_b128 v[168:171], v243 offset:51200
	ds_read_b128 v[172:175], v243 offset:52224
	ds_read_b128 v[176:179], v243 offset:53248
	ds_read_b128 v[180:183], v243 offset:54272
	ds_read_b128 v[184:187], v243 offset:55296
	ds_read_b128 v[188:191], v243 offset:56320
	global_load_lds_dwordx4 v[198:199], off
	v_lshl_add_u64 v[198:199], v[200:201], 0, s[22:23]
	s_add_i32 m0, s12, 0x2000
	s_add_i32 s12, s15, s55
	global_load_lds_dwordx4 v[198:199], off
	v_lshl_add_u64 v[198:199], v[202:203], 0, s[22:23]
	s_mov_b32 m0, s12
	s_nop 0
	global_load_lds_dwordx4 v[198:199], off
	v_lshl_add_u64 v[198:199], v[204:205], 0, s[22:23]
	s_add_i32 m0, s12, 0x2000
	s_nop 0
	global_load_lds_dwordx4 v[198:199], off
	v_lshl_add_u64 v[198:199], v[206:207], 0, s[22:23]
	s_mov_b32 m0, s17
	s_nop 0
	global_load_lds_dwordx4 v[198:199], off
	v_lshl_add_u64 v[198:199], v[208:209], 0, s[22:23]
	s_mov_b32 m0, s27
	s_nop 0
	global_load_lds_dwordx4 v[198:199], off
	s_waitcnt vmcnt(8)
	s_waitcnt lgkmcnt(0)
	s_barrier
	s_setprio 1
	s_waitcnt lgkmcnt(0)
	v_mfma_f32_16x16x32_bf16 v[60:63], v[128:131], v[160:163], v[60:63]
	v_mfma_f32_16x16x32_bf16 v[60:63], v[132:135], v[164:167], v[60:63]
	v_mfma_f32_16x16x32_bf16 v[56:59], v[136:139], v[160:163], v[56:59]
	v_mfma_f32_16x16x32_bf16 v[56:59], v[140:143], v[164:167], v[56:59]
	v_mfma_f32_16x16x32_bf16 v[44:47], v[128:131], v[168:171], v[44:47]
	v_mfma_f32_16x16x32_bf16 v[44:47], v[132:135], v[172:175], v[44:47]
	v_mfma_f32_16x16x32_bf16 v[40:43], v[136:139], v[168:171], v[40:43]
	v_mfma_f32_16x16x32_bf16 v[40:43], v[140:143], v[172:175], v[40:43]
	v_mfma_f32_16x16x32_bf16 v[28:31], v[128:131], v[176:179], v[28:31]
	v_mfma_f32_16x16x32_bf16 v[28:31], v[132:135], v[180:183], v[28:31]
	v_mfma_f32_16x16x32_bf16 v[24:27], v[136:139], v[176:179], v[24:27]
	v_mfma_f32_16x16x32_bf16 v[24:27], v[140:143], v[180:183], v[24:27]
	v_mfma_f32_16x16x32_bf16 v[12:15], v[128:131], v[184:187], v[12:15]
	v_mfma_f32_16x16x32_bf16 v[12:15], v[132:135], v[188:191], v[12:15]
	v_mfma_f32_16x16x32_bf16 v[8:11], v[136:139], v[184:187], v[8:11]
	v_mfma_f32_16x16x32_bf16 v[8:11], v[140:143], v[188:191], v[8:11]
	s_setprio 0
	s_setprio 1
	v_mfma_f32_16x16x32_bf16 v[52:55], v[144:147], v[160:163], v[52:55]
	v_mfma_f32_16x16x32_bf16 v[52:55], v[148:151], v[164:167], v[52:55]
	v_mfma_f32_16x16x32_bf16 v[48:51], v[152:155], v[160:163], v[48:51]
	v_mfma_f32_16x16x32_bf16 v[48:51], v[156:159], v[164:167], v[48:51]
	v_mfma_f32_16x16x32_bf16 v[36:39], v[144:147], v[168:171], v[36:39]
	v_mfma_f32_16x16x32_bf16 v[36:39], v[148:151], v[172:175], v[36:39]
	v_mfma_f32_16x16x32_bf16 v[32:35], v[152:155], v[168:171], v[32:35]
	v_mfma_f32_16x16x32_bf16 v[32:35], v[156:159], v[172:175], v[32:35]
	v_mfma_f32_16x16x32_bf16 v[20:23], v[144:147], v[176:179], v[20:23]
	v_mfma_f32_16x16x32_bf16 v[20:23], v[148:151], v[180:183], v[20:23]
	v_mfma_f32_16x16x32_bf16 v[16:19], v[152:155], v[176:179], v[16:19]
	v_mfma_f32_16x16x32_bf16 v[16:19], v[156:159], v[180:183], v[16:19]
	v_mfma_f32_16x16x32_bf16 v[4:7], v[144:147], v[184:187], v[4:7]
	v_mfma_f32_16x16x32_bf16 v[4:7], v[148:151], v[188:191], v[4:7]
	v_mfma_f32_16x16x32_bf16 v[0:3], v[152:155], v[184:187], v[0:3]
	v_mfma_f32_16x16x32_bf16 v[0:3], v[156:159], v[188:191], v[0:3]
	s_setprio 0
	s_barrier
	s_add_i32 s12, s36, 2
	s_add_u32 s40, s40, 0x100
	s_addc_u32 s41, s41, 0
	s_cmp_ge_u32 s36, s16
	s_mov_b32 s36, s12
	s_cbranch_scc1 .LBB0_191

; #define PG8_STAGE(bufoff, gbase, voff) do { _Pragma("unroll") for (int _i = 0; _i < 2; ++_i) \
;         __builtin_amdgcn_global_load_lds((const unsigned*)((const char*)(gbase) + (voff)[_i]), (PG8_LAS unsigned*)(lds + (bufoff) + ldsw + _i * 8192), 16, 0, 0); } while (0)
; #define PG8_LDA(dst, b, h) do { _Pragma("unroll") for (int m = 0; m < 4; ++m) _Pragma("unroll") for (int k = 0; k < 2; ++k) dst[m][k] = *(const PG8_LAS bf16x8*)(lds + PG8_SA(b, h) + aoff + m * 2048 + k * 1024); } while (0)
; #define PG8_LDB(dst, b, h) do { _Pragma("unroll") for (int n = 0; n < 2; ++n) _Pragma("unroll") for (int k = 0; k < 2; ++k) dst[n][k] = *(const PG8_LAS bf16x8*)(lds + PG8_SB(b, h) + boff + n * 2048 + k * 1024); } while (0)
; #define PG8_WAIT_V(n) asm volatile("s_waitcnt vmcnt(" #n ")" ::: "memory")
; #define PG8_WAIT_L(n) asm volatile("s_waitcnt lgkmcnt(" #n ")" ::: "memory")
; #define PG8_BAR __builtin_amdgcn_s_barrier()
; #define PG8_SCHED __builtin_amdgcn_sched_barrier(0)
; template <class Epi, class Sched, bool ALIGN_EPI = false, bool SP2 = false>
; __device__ __forceinline__ void gemm_phase(PG8_LAS unsigned char* lds, const Gemm g, const Sched& S, const Epi& E) {
;     ...
;             const char* a1 = cA + (g.gstrA ? (size_t)(t >> 2) * g.gstrA + (size_t)(t & 3) * kstep : (size_t)t * kstep) + kstep;
;             const char* a2 = last ? nA : cA + (g.gstrA ? (size_t)((t + 2) >> 2) * g.gstrA + (size_t)((t + 2) & 3) * kstep : (size_t)(t + 2) * kstep); const char* b2 = last ? nB : cB + (size_t)(t + 2) * kstep;
;             const char* a3 = a2 + kstep; const char* b3 = b2 + kstep;
;             if (last && has_next) S.a_ready(nxt);
;             if constexpr (Epi::HAS_PREFETCH) { if (t == nt - 4) E.prefetch(cur, tid, wid); }
;             if constexpr (SP2) {
;             PG8_LDB(B0, 0, 0); PG8_LDB(B1, 0, 1); PG8_SCHED; PG8_LDA(At, 0, 0); PG8_STAGE(PG8_SA(1, 1), a1 + hstepA, voffA);
;             PG8_WAIT_V(8); PG8_WAIT_L(0); PG8_BAR; PG8_MMA(0, 0, At, B0); PG8_MMA(0, 1, At, B1); PG8_BAR; PG8_SCHED;
;             PG8_LDA(At, 0, 1); PG8_STAGE(PG8_SB(0, 0), b2, voffB); PG8_STAGE(PG8_SB(0, 1), b2 + hstep, voffB); PG8_STAGE(PG8_SA(0, 0), a2, voffA);
;             PG8_WAIT_V(8); PG8_WAIT_L(0); PG8_BAR; PG8_MMA(1, 0, At, B0); PG8_MMA(1, 1, At, B1); PG8_BAR; PG8_SCHED;
.LBB0_369:
	s_add_u32 s14, s68, 0xfffc0080
	s_addc_u32 s15, s69, -1
	s_add_i32 s59, 0, 0x10000
	s_cmp_eq_u32 s52, 12
	s_cselect_b32 s15, s24, s15
	s_cselect_b32 s14, s26, s14
	s_cselect_b32 s41, s30, s37
	s_cselect_b32 s40, s34, s36
	s_add_i32 s61, 0, 0x14000
	v_add_u32_e32 v162, s59, v139
	v_add_u32_e32 v178, s61, v139
	ds_read_b128 v[150:153], v162
	ds_read_b128 v[154:157], v162 offset:1024
	ds_read_b128 v[158:161], v162 offset:2048
	ds_read_b128 v[162:165], v162 offset:3072
	ds_read_b128 v[166:169], v178
	ds_read_b128 v[170:173], v178 offset:1024
	ds_read_b128 v[174:177], v178 offset:2048
	ds_read_b128 v[178:181], v178 offset:3072
	v_lshl_add_u64 v[210:211], s[68:69], 0, v[134:135]
	s_add_i32 m0, s17, 0xc000
	ds_read_b128 v[182:185], v149
	ds_read_b128 v[186:189], v149 offset:1024
	ds_read_b128 v[190:193], v149 offset:2048
	ds_read_b128 v[194:197], v149 offset:3072
	ds_read_b128 v[198:201], v149 offset:4096
	ds_read_b128 v[202:205], v149 offset:5120
	ds_read_b128 v[206:209], v149 offset:6144
	ds_read_b128 v[214:217], v149 offset:7168
	global_load_lds_dwordx4 v[210:211], off
	v_lshl_add_u64 v[210:211], s[68:69], 0, v[136:137]
	s_add_i32 m0, s17, 0xe000
	s_nop 0
	global_load_lds_dwordx4 v[210:211], off
	s_waitcnt vmcnt(8)
	s_waitcnt lgkmcnt(0)
	s_barrier
	s_setprio 1
	s_waitcnt lgkmcnt(0)
	v_mfma_f32_16x16x32_bf16 v[124:127], v[150:153], v[182:185], v[124:127]
	v_mfma_f32_16x16x32_bf16 v[124:127], v[154:157], v[186:189], v[124:127]
	v_mfma_f32_16x16x32_bf16 v[116:119], v[158:161], v[182:185], v[116:119]
	v_mfma_f32_16x16x32_bf16 v[116:119], v[162:165], v[186:189], v[116:119]
	v_mfma_f32_16x16x32_bf16 v[108:111], v[150:153], v[190:193], v[108:111]
	v_mfma_f32_16x16x32_bf16 v[108:111], v[154:157], v[194:197], v[108:111]
	v_mfma_f32_16x16x32_bf16 v[100:103], v[158:161], v[190:193], v[100:103]
	v_mfma_f32_16x16x32_bf16 v[100:103], v[162:165], v[194:197], v[100:103]
	v_mfma_f32_16x16x32_bf16 v[92:95], v[150:153], v[198:201], v[92:95]
	v_mfma_f32_16x16x32_bf16 v[92:95], v[154:157], v[202:205], v[92:95]
	v_mfma_f32_16x16x32_bf16 v[84:87], v[158:161], v[198:201], v[84:87]
	v_mfma_f32_16x16x32_bf16 v[84:87], v[162:165], v[202:205], v[84:87]
	v_mfma_f32_16x16x32_bf16 v[76:79], v[150:153], v[206:209], v[76:79]
	v_mfma_f32_16x16x32_bf16 v[76:79], v[154:157], v[214:217], v[76:79]
	v_mfma_f32_16x16x32_bf16 v[68:71], v[158:161], v[206:209], v[68:71]
	v_mfma_f32_16x16x32_bf16 v[68:71], v[162:165], v[214:217], v[68:71]
	s_setprio 0
	s_setprio 1
	v_mfma_f32_16x16x32_bf16 v[120:123], v[166:169], v[182:185], v[120:123]
	v_mfma_f32_16x16x32_bf16 v[120:123], v[170:173], v[186:189], v[120:123]
	v_mfma_f32_16x16x32_bf16 v[112:115], v[174:177], v[182:185], v[112:115]
	v_mfma_f32_16x16x32_bf16 v[112:115], v[178:181], v[186:189], v[112:115]
	v_mfma_f32_16x16x32_bf16 v[104:107], v[166:169], v[190:193], v[104:107]
	v_mfma_f32_16x16x32_bf16 v[104:107], v[170:173], v[194:197], v[104:107]
	v_mfma_f32_16x16x32_bf16 v[96:99], v[174:177], v[190:193], v[96:99]
	v_mfma_f32_16x16x32_bf16 v[96:99], v[178:181], v[194:197], v[96:99]
	v_mfma_f32_16x16x32_bf16 v[88:91], v[166:169], v[198:201], v[88:91]
	v_mfma_f32_16x16x32_bf16 v[88:91], v[170:173], v[202:205], v[88:91]
	v_mfma_f32_16x16x32_bf16 v[80:83], v[174:177], v[198:201], v[80:83]
	v_mfma_f32_16x16x32_bf16 v[80:83], v[178:181], v[202:205], v[80:83]
	v_mfma_f32_16x16x32_bf16 v[72:75], v[166:169], v[206:209], v[72:75]
	v_mfma_f32_16x16x32_bf16 v[72:75], v[170:173], v[214:217], v[72:75]
	v_mfma_f32_16x16x32_bf16 v[64:67], v[174:177], v[206:209], v[64:67]
	v_mfma_f32_16x16x32_bf16 v[64:67], v[178:181], v[214:217], v[64:67]
	s_setprio 0
	s_barrier
	s_add_i32 s59, s59, s2
	v_lshl_add_u64 v[210:211], s[40:41], 0, v[212:213]
	s_mov_b32 m0, s59
	ds_read_b128 v[182:185], v149 offset:16384
	ds_read_b128 v[186:189], v149 offset:17408
	ds_read_b128 v[190:193], v149 offset:18432
	ds_read_b128 v[194:197], v149 offset:19456
	ds_read_b128 v[198:201], v149 offset:20480
	ds_read_b128 v[202:205], v149 offset:21504
	ds_read_b128 v[206:209], v149 offset:22528
	ds_read_b128 v[214:217], v149 offset:23552
	global_load_lds_dwordx4 v[210:211], off
	s_add_i32 m0, s59, 0x2000
	s_add_u32 s70, s40, 0x40000
	v_lshl_add_u64 v[218:219], s[40:41], 0, v[128:129]
	s_addc_u32 s71, s41, 0
	s_add_i32 s59, s61, s2
	global_load_lds_dwordx4 v[218:219], off
	v_lshl_add_u64 v[220:221], s[70:71], 0, v[212:213]
	s_mov_b32 m0, s59
	v_lshl_add_u64 v[222:223], s[14:15], 0, v[130:131]
	global_load_lds_dwordx4 v[220:221], off
	v_lshl_add_u64 v[220:221], s[70:71], 0, v[128:129]
	s_add_i32 m0, s59, 0x2000
	s_nop 0
	global_load_lds_dwordx4 v[220:221], off
	v_lshl_add_u64 v[220:221], s[14:15], 0, v[132:133]
	s_mov_b32 m0, s17
	s_nop 0
	global_load_lds_dwordx4 v[220:221], off
	s_mov_b32 m0, s18
	s_nop 0
	global_load_lds_dwordx4 v[222:223], off
	s_waitcnt vmcnt(8)
	s_waitcnt lgkmcnt(0)
	s_barrier
; #define PG8_STAGE(bufoff, gbase, voff) do { _Pragma("unroll") for (int _i = 0; _i < 2; ++_i) \
;         __builtin_amdgcn_global_load_lds((const unsigned*)((const char*)(gbase) + (voff)[_i]), (PG8_LAS unsigned*)(lds + (bufoff) + ldsw + _i * 8192), 16, 0, 0); } while (0)
; #define PG8_LDA(dst, b, h) do { _Pragma("unroll") for (int m = 0; m < 4; ++m) _Pragma("unroll") for (int k = 0; k < 2; ++k) dst[m][k] = *(const PG8_LAS bf16x8*)(lds + PG8_SA(b, h) + aoff + m * 2048 + k * 1024); } while (0)
; #define PG8_LDB(dst, b, h) do { _Pragma("unroll") for (int n = 0; n < 2; ++n) _Pragma("unroll") for (int k = 0; k < 2; ++k) dst[n][k] = *(const PG8_LAS bf16x8*)(lds + PG8_SB(b, h) + boff + n * 2048 + k * 1024); } while (0)
; #define PG8_MMA(ai, bj, At, Bt) do { __builtin_amdgcn_s_setprio(1); _Pragma("unroll") for (int m = 0; m < 4; ++m) _Pragma("unroll") for (int n = 0; n < 2; ++n) _Pragma("unroll") for (int k = 0; k < 2; ++k) \
;         acc[ai][bj][m][n] = __builtin_amdgcn_mfma_f32_16x16x32_bf16(Bt[n][k], At[m][k], acc[ai][bj][m][n], 0, 0, 0); __builtin_amdgcn_s_setprio(0); } while (0)
; #define PG8_WAIT_V(n) asm volatile("s_waitcnt vmcnt(" #n ")" ::: "memory")
; #define PG8_WAIT_L(n) asm volatile("s_waitcnt lgkmcnt(" #n ")" ::: "memory")
; #define PG8_BAR __builtin_amdgcn_s_barrier()
; #define PG8_SCHED __builtin_amdgcn_sched_barrier(0)
; template <class Epi, class Sched, bool ALIGN_EPI = false, bool SP2 = false>
; __device__ __forceinline__ void gemm_phase(PG8_LAS unsigned char* lds, const Gemm g, const Sched& S, const Epi& E) {
;     ...
;             PG8_WAIT_V(8); PG8_WAIT_L(0); PG8_BAR; PG8_MMA(1, 0, At, B0); PG8_MMA(1, 1, At, B1); PG8_BAR; PG8_SCHED;
;             PG8_LDB(B0, 1, 0); PG8_LDB(B1, 1, 1); PG8_SCHED; PG8_LDA(At, 1, 0); PG8_STAGE(PG8_SA(0, 1), a2 + hstepA, voffA);
;             PG8_WAIT_V(8); PG8_WAIT_L(0); PG8_BAR; PG8_MMA(0, 0, At, B0); PG8_MMA(0, 1, At, B1); PG8_BAR; PG8_SCHED;
	s_setprio 1
	s_waitcnt lgkmcnt(0)
	v_mfma_f32_16x16x32_bf16 v[60:63], v[150:153], v[182:185], v[60:63]
	v_mfma_f32_16x16x32_bf16 v[60:63], v[154:157], v[186:189], v[60:63]
	v_mfma_f32_16x16x32_bf16 v[52:55], v[158:161], v[182:185], v[52:55]
	v_mfma_f32_16x16x32_bf16 v[52:55], v[162:165], v[186:189], v[52:55]
	v_mfma_f32_16x16x32_bf16 v[44:47], v[150:153], v[190:193], v[44:47]
	v_mfma_f32_16x16x32_bf16 v[44:47], v[154:157], v[194:197], v[44:47]
	v_mfma_f32_16x16x32_bf16 v[36:39], v[158:161], v[190:193], v[36:39]
	v_mfma_f32_16x16x32_bf16 v[36:39], v[162:165], v[194:197], v[36:39]
	v_mfma_f32_16x16x32_bf16 v[28:31], v[150:153], v[198:201], v[28:31]
	v_mfma_f32_16x16x32_bf16 v[28:31], v[154:157], v[202:205], v[28:31]
	v_mfma_f32_16x16x32_bf16 v[20:23], v[158:161], v[198:201], v[20:23]
	v_mfma_f32_16x16x32_bf16 v[20:23], v[162:165], v[202:205], v[20:23]
	v_mfma_f32_16x16x32_bf16 v[12:15], v[150:153], v[206:209], v[12:15]
	v_mfma_f32_16x16x32_bf16 v[12:15], v[154:157], v[214:217], v[12:15]
	v_mfma_f32_16x16x32_bf16 v[4:7], v[158:161], v[206:209], v[4:7]
	v_mfma_f32_16x16x32_bf16 v[4:7], v[162:165], v[214:217], v[4:7]
	s_setprio 0
	s_setprio 1
	v_mfma_f32_16x16x32_bf16 v[56:59], v[166:169], v[182:185], v[56:59]
	v_mfma_f32_16x16x32_bf16 v[56:59], v[170:173], v[186:189], v[56:59]
	v_mfma_f32_16x16x32_bf16 v[48:51], v[174:177], v[182:185], v[48:51]
	v_mfma_f32_16x16x32_bf16 v[48:51], v[178:181], v[186:189], v[48:51]
	v_mfma_f32_16x16x32_bf16 v[40:43], v[166:169], v[190:193], v[40:43]
	v_mfma_f32_16x16x32_bf16 v[40:43], v[170:173], v[194:197], v[40:43]
	v_mfma_f32_16x16x32_bf16 v[32:35], v[174:177], v[190:193], v[32:35]
	v_mfma_f32_16x16x32_bf16 v[32:35], v[178:181], v[194:197], v[32:35]
	v_mfma_f32_16x16x32_bf16 v[24:27], v[166:169], v[198:201], v[24:27]
	v_mfma_f32_16x16x32_bf16 v[24:27], v[170:173], v[202:205], v[24:27]
	v_mfma_f32_16x16x32_bf16 v[16:19], v[174:177], v[198:201], v[16:19]
	v_mfma_f32_16x16x32_bf16 v[16:19], v[178:181], v[202:205], v[16:19]
	v_mfma_f32_16x16x32_bf16 v[8:11], v[166:169], v[206:209], v[8:11]
	v_mfma_f32_16x16x32_bf16 v[8:11], v[170:173], v[214:217], v[8:11]
	v_mfma_f32_16x16x32_bf16 v[0:3], v[174:177], v[206:209], v[0:3]
	v_mfma_f32_16x16x32_bf16 v[0:3], v[178:181], v[214:217], v[0:3]
	s_setprio 0
	s_barrier
	s_add_i32 s59, 0, 0x18000
	s_add_i32 s61, 0, 0x1c000
	v_add_u32_e32 v162, s59, v139
	v_add_u32_e32 v178, s61, v139
	ds_read_b128 v[150:153], v162
	ds_read_b128 v[154:157], v162 offset:1024
	ds_read_b128 v[158:161], v162 offset:2048
	ds_read_b128 v[162:165], v162 offset:3072
	ds_read_b128 v[166:169], v178
	ds_read_b128 v[170:173], v178 offset:1024
	ds_read_b128 v[174:177], v178 offset:2048
	ds_read_b128 v[178:181], v178 offset:3072
	s_add_u32 s14, s14, 0x40000
	s_addc_u32 s15, s15, 0
	s_mov_b32 m0, s20
	v_lshl_add_u64 v[224:225], s[14:15], 0, v[132:133]
	ds_read_b128 v[182:185], v149 offset:32768
	ds_read_b128 v[186:189], v149 offset:33792
	ds_read_b128 v[190:193], v149 offset:34816
	ds_read_b128 v[194:197], v149 offset:35840
	ds_read_b128 v[198:201], v149 offset:36864
	ds_read_b128 v[202:205], v149 offset:37888
	ds_read_b128 v[206:209], v149 offset:38912
	ds_read_b128 v[214:217], v149 offset:39936
	global_load_lds_dwordx4 v[224:225], off
	v_lshl_add_u64 v[224:225], s[14:15], 0, v[130:131]
	s_mov_b32 m0, s21
	s_nop 0
	global_load_lds_dwordx4 v[224:225], off
	s_waitcnt vmcnt(8)
	s_waitcnt lgkmcnt(0)
	s_barrier
	s_setprio 1
	s_waitcnt lgkmcnt(0)
	v_mfma_f32_16x16x32_bf16 v[124:127], v[150:153], v[182:185], v[124:127]
	v_mfma_f32_16x16x32_bf16 v[124:127], v[154:157], v[186:189], v[124:127]
	v_mfma_f32_16x16x32_bf16 v[116:119], v[158:161], v[182:185], v[116:119]
	v_mfma_f32_16x16x32_bf16 v[116:119], v[162:165], v[186:189], v[116:119]
	v_mfma_f32_16x16x32_bf16 v[108:111], v[150:153], v[190:193], v[108:111]
	v_mfma_f32_16x16x32_bf16 v[108:111], v[154:157], v[194:197], v[108:111]
	v_mfma_f32_16x16x32_bf16 v[100:103], v[158:161], v[190:193], v[100:103]
	v_mfma_f32_16x16x32_bf16 v[100:103], v[162:165], v[194:197], v[100:103]
	v_mfma_f32_16x16x32_bf16 v[92:95], v[150:153], v[198:201], v[92:95]
	v_mfma_f32_16x16x32_bf16 v[92:95], v[154:157], v[202:205], v[92:95]
	v_mfma_f32_16x16x32_bf16 v[84:87], v[158:161], v[198:201], v[84:87]
	v_mfma_f32_16x16x32_bf16 v[84:87], v[162:165], v[202:205], v[84:87]
	v_mfma_f32_16x16x32_bf16 v[76:79], v[150:153], v[206:209], v[76:79]
	v_mfma_f32_16x16x32_bf16 v[76:79], v[154:157], v[214:217], v[76:79]
	v_mfma_f32_16x16x32_bf16 v[68:71], v[158:161], v[206:209], v[68:71]
	v_mfma_f32_16x16x32_bf16 v[68:71], v[162:165], v[214:217], v[68:71]
	s_setprio 0
	s_setprio 1
	v_mfma_f32_16x16x32_bf16 v[120:123], v[166:169], v[182:185], v[120:123]
	v_mfma_f32_16x16x32_bf16 v[120:123], v[170:173], v[186:189], v[120:123]
	v_mfma_f32_16x16x32_bf16 v[112:115], v[174:177], v[182:185], v[112:115]
	v_mfma_f32_16x16x32_bf16 v[112:115], v[178:181], v[186:189], v[112:115]
	v_mfma_f32_16x16x32_bf16 v[104:107], v[166:169], v[190:193], v[104:107]
	v_mfma_f32_16x16x32_bf16 v[104:107], v[170:173], v[194:197], v[104:107]
	v_mfma_f32_16x16x32_bf16 v[96:99], v[174:177], v[190:193], v[96:99]
	v_mfma_f32_16x16x32_bf16 v[96:99], v[178:181], v[194:197], v[96:99]
	v_mfma_f32_16x16x32_bf16 v[88:91], v[166:169], v[198:201], v[88:91]
	v_mfma_f32_16x16x32_bf16 v[88:91], v[170:173], v[202:205], v[88:91]
	v_mfma_f32_16x16x32_bf16 v[80:83], v[174:177], v[198:201], v[80:83]
	v_mfma_f32_16x16x32_bf16 v[80:83], v[178:181], v[202:205], v[80:83]
	v_mfma_f32_16x16x32_bf16 v[72:75], v[166:169], v[206:209], v[72:75]
	v_mfma_f32_16x16x32_bf16 v[72:75], v[170:173], v[214:217], v[72:75]
	v_mfma_f32_16x16x32_bf16 v[64:67], v[174:177], v[206:209], v[64:67]
	v_mfma_f32_16x16x32_bf16 v[64:67], v[178:181], v[214:217], v[64:67]
	s_setprio 0
	s_barrier
; #define PG8_STAGE(bufoff, gbase, voff) do { _Pragma("unroll") for (int _i = 0; _i < 2; ++_i) \
;         __builtin_amdgcn_global_load_lds((const unsigned*)((const char*)(gbase) + (voff)[_i]), (PG8_LAS unsigned*)(lds + (bufoff) + ldsw + _i * 8192), 16, 0, 0); } while (0)
; #define PG8_LDA(dst, b, h) do { _Pragma("unroll") for (int m = 0; m < 4; ++m) _Pragma("unroll") for (int k = 0; k < 2; ++k) dst[m][k] = *(const PG8_LAS bf16x8*)(lds + PG8_SA(b, h) + aoff + m * 2048 + k * 1024); } while (0)
; #define PG8_MMA(ai, bj, At, Bt) do { __builtin_amdgcn_s_setprio(1); _Pragma("unroll") for (int m = 0; m < 4; ++m) _Pragma("unroll") for (int n = 0; n < 2; ++n) _Pragma("unroll") for (int k = 0; k < 2; ++k) \
;         acc[ai][bj][m][n] = __builtin_amdgcn_mfma_f32_16x16x32_bf16(Bt[n][k], At[m][k], acc[ai][bj][m][n], 0, 0, 0); __builtin_amdgcn_s_setprio(0); } while (0)
; #define PG8_WAIT_V(n) asm volatile("s_waitcnt vmcnt(" #n ")" ::: "memory")
; #define PG8_WAIT_L(n) asm volatile("s_waitcnt lgkmcnt(" #n ")" ::: "memory")
; #define PG8_BAR __builtin_amdgcn_s_barrier()
; #define PG8_SCHED __builtin_amdgcn_sched_barrier(0)
; template <class Epi, class Sched, bool ALIGN_EPI = false, bool SP2 = false>
; __device__ __forceinline__ void gemm_phase(PG8_LAS unsigned char* lds, const Gemm g, const Sched& S, const Epi& E) {
;     ...
;         for (int t = 0; t < nt; t += 2) {
;     ...
;             PG8_LDA(At, 1, 1); PG8_STAGE(PG8_SB(1, 0), b3, voffB); PG8_STAGE(PG8_SB(1, 1), b3 + hstep, voffB); PG8_STAGE(PG8_SA(1, 0), a3, voffA);
;             PG8_WAIT_V(8); PG8_WAIT_L(0); PG8_BAR; PG8_MMA(1, 0, At, B0); PG8_MMA(1, 1, At, B1); PG8_BAR; PG8_SCHED;
;     ...
;         if constexpr (ALIGN_EPI) { if (wr == 0) PG8_BAR; }
	s_add_i32 s14, s59, s2
	v_lshl_add_u64 v[210:211], v[210:211], 0, s[22:23]
	s_mov_b32 m0, s14
	ds_read_b128 v[182:185], v149 offset:49152
	ds_read_b128 v[186:189], v149 offset:50176
	ds_read_b128 v[190:193], v149 offset:51200
	ds_read_b128 v[194:197], v149 offset:52224
	ds_read_b128 v[198:201], v149 offset:53248
	ds_read_b128 v[202:205], v149 offset:54272
	ds_read_b128 v[206:209], v149 offset:55296
	ds_read_b128 v[214:217], v149 offset:56320
	global_load_lds_dwordx4 v[210:211], off
	s_add_i32 m0, s14, 0x2000
	s_add_u32 s14, s40, 0x40080
	v_lshl_add_u64 v[210:211], v[218:219], 0, s[22:23]
	s_addc_u32 s15, s41, 0
	s_add_i32 s40, s61, s2
	global_load_lds_dwordx4 v[210:211], off
	v_lshl_add_u64 v[210:211], s[14:15], 0, v[212:213]
	s_mov_b32 m0, s40
	s_nop 0
	global_load_lds_dwordx4 v[210:211], off
	v_lshl_add_u64 v[210:211], s[14:15], 0, v[128:129]
	s_add_i32 m0, s40, 0x2000
	s_nop 0
	global_load_lds_dwordx4 v[210:211], off
	v_lshl_add_u64 v[210:211], v[220:221], 0, s[22:23]
	s_mov_b32 m0, s25
	s_nop 0
	global_load_lds_dwordx4 v[210:211], off
	v_lshl_add_u64 v[210:211], v[222:223], 0, s[22:23]
	s_mov_b32 m0, s27
	s_nop 0
	global_load_lds_dwordx4 v[210:211], off
	s_waitcnt vmcnt(8)
	s_waitcnt lgkmcnt(0)
	s_barrier
	s_setprio 1
	s_waitcnt lgkmcnt(0)
	v_mfma_f32_16x16x32_bf16 v[60:63], v[150:153], v[182:185], v[60:63]
	v_mfma_f32_16x16x32_bf16 v[60:63], v[154:157], v[186:189], v[60:63]
	v_mfma_f32_16x16x32_bf16 v[52:55], v[158:161], v[182:185], v[52:55]
	v_mfma_f32_16x16x32_bf16 v[52:55], v[162:165], v[186:189], v[52:55]
	v_mfma_f32_16x16x32_bf16 v[44:47], v[150:153], v[190:193], v[44:47]
	v_mfma_f32_16x16x32_bf16 v[44:47], v[154:157], v[194:197], v[44:47]
	v_mfma_f32_16x16x32_bf16 v[36:39], v[158:161], v[190:193], v[36:39]
	v_mfma_f32_16x16x32_bf16 v[36:39], v[162:165], v[194:197], v[36:39]
	v_mfma_f32_16x16x32_bf16 v[28:31], v[150:153], v[198:201], v[28:31]
	v_mfma_f32_16x16x32_bf16 v[28:31], v[154:157], v[202:205], v[28:31]
	v_mfma_f32_16x16x32_bf16 v[20:23], v[158:161], v[198:201], v[20:23]
	v_mfma_f32_16x16x32_bf16 v[20:23], v[162:165], v[202:205], v[20:23]
	v_mfma_f32_16x16x32_bf16 v[12:15], v[150:153], v[206:209], v[12:15]
	v_mfma_f32_16x16x32_bf16 v[12:15], v[154:157], v[214:217], v[12:15]
	v_mfma_f32_16x16x32_bf16 v[4:7], v[158:161], v[206:209], v[4:7]
	v_mfma_f32_16x16x32_bf16 v[4:7], v[162:165], v[214:217], v[4:7]
	s_setprio 0
	s_setprio 1
	v_mfma_f32_16x16x32_bf16 v[56:59], v[166:169], v[182:185], v[56:59]
	v_mfma_f32_16x16x32_bf16 v[56:59], v[170:173], v[186:189], v[56:59]
	v_mfma_f32_16x16x32_bf16 v[48:51], v[174:177], v[182:185], v[48:51]
	v_mfma_f32_16x16x32_bf16 v[48:51], v[178:181], v[186:189], v[48:51]
	v_mfma_f32_16x16x32_bf16 v[40:43], v[166:169], v[190:193], v[40:43]
	v_mfma_f32_16x16x32_bf16 v[40:43], v[170:173], v[194:197], v[40:43]
	v_mfma_f32_16x16x32_bf16 v[32:35], v[174:177], v[190:193], v[32:35]
	v_mfma_f32_16x16x32_bf16 v[32:35], v[178:181], v[194:197], v[32:35]
	v_mfma_f32_16x16x32_bf16 v[24:27], v[166:169], v[198:201], v[24:27]
	v_mfma_f32_16x16x32_bf16 v[24:27], v[170:173], v[202:205], v[24:27]
	v_mfma_f32_16x16x32_bf16 v[16:19], v[174:177], v[198:201], v[16:19]
	v_mfma_f32_16x16x32_bf16 v[16:19], v[178:181], v[202:205], v[16:19]
	v_mfma_f32_16x16x32_bf16 v[8:11], v[166:169], v[206:209], v[8:11]
	v_mfma_f32_16x16x32_bf16 v[8:11], v[170:173], v[214:217], v[8:11]
	v_mfma_f32_16x16x32_bf16 v[0:3], v[174:177], v[206:209], v[0:3]
	v_mfma_f32_16x16x32_bf16 v[0:3], v[178:181], v[214:217], v[0:3]
	s_setprio 0
	s_barrier
	s_add_i32 s52, s52, 2
	s_add_u32 s68, s68, 0x100
	s_addc_u32 s69, s69, 0
	s_add_u32 s36, s36, 0x100
	s_addc_u32 s37, s37, 0
	s_cmp_gt_u32 s52, 13
	s_cbranch_scc0 .LBB0_369
	s_and_b64 vcc, exec, s[56:57]
	s_cbranch_vccz .LBB0_372
	s_barrier
